# v071 with sc1 (write-through) on the hand-written epilogue stores
# baseline (speedup 1.0000x reference)
; __device__ __forceinline__ unsigned cvt_pk_bf16(float lo, float hi) { unsigned r; asm volatile("v_cvt_pk_bf16_f32 %0, %1, %2" : "=v"(r) : "v"(lo), "v"(hi)); return r; }
; __device__ __forceinline__ float fast_sigmoid(float x) { return __builtin_amdgcn_rcpf(1.0f + __builtin_amdgcn_exp2f(-x * LOG2E)); }
;     __device__ __forceinline__ void operator()(EPI_ARGS) const {
;     ...
; #pragma unroll
;             for (int ai = 0; ai < 2; ++ai)
; #pragma unroll
;                 for (int m = 0; m < 4; ++m) {
;                     const float rs = I8 ? rtab[wr * 64 + fr + ai * HALF + m * 16] : 1.0f;
;                     f32x4 o[2];
; #pragma unroll
;                     for (int n = 0; n < 2; ++n) { f32x4 a = acc[ai][0][m][n], b = acc[ai][1][m][n];
;                         if (I8) { const i32x4 ia = __builtin_bit_cast(i32x4, a), ib = __builtin_bit_cast(i32x4, b);
;                             a = (f32x4){(float)ia[0], (float)ia[1], (float)ia[2], (float)ia[3]} * (sb[0][n] * rs); b = (f32x4){(float)ib[0], (float)ib[1], (float)ib[2], (float)ib[3]} * (sb[1][n] * rs); }
; #pragma unroll
;                         for (int e = 0; e < 4; ++e) o[n][e] = glu ? a[e] * fast_sigmoid(b[e]) : a[e] * b[e]; }
;                     u32x4 w; w.x = cvt_pk_bf16(o[0][0], o[0][1]); w.y = cvt_pk_bf16(o[0][2], o[0][3]); w.z = cvt_pk_bf16(o[1][0], o[1][1]); w.w = cvt_pk_bf16(o[1][2], o[1][3]);
;                     *(u32x4*)(base + (size_t)(row0 + ai * HALF + m * 16) * CWID) = w; }
.LBB0_564:
	s_nop 7
	v_lshl_add_u32 v245, s0, 8, v151
	v_mul_u32_u24_e32 v245, 0x1080, v245
	v_bfe_u32 v246, v0, 6, 2
	v_bfe_u32 v255, v0, 4, 2
	v_lshlrev_b32_e32 v246, 6, v246
	v_lshl_add_u32 v246, v255, 4, v246
	v_add_u32_e32 v245, v245, v246
	s_cmp_gt_i32 s91, 15
	s_cbranch_scc1 .Lmy_p1b_bg
	s_lshl_b32 s0, s91, 8
	v_add_u32_e32 v245, s0, v245
	v_readlane_b32 s0, v244, 47
	v_readlane_b32 s1, v244, 48
	s_nop 4
	v_pk_mul_f32 v[126:127], v[126:127], v[122:123]
	v_pk_mul_f32 v[128:129], v[128:129], v[124:125]
	v_cvt_pk_bf16_f32 v136, v126, v127
	v_cvt_pk_bf16_f32 v137, v128, v129
	v_pk_mul_f32 v[118:119], v[118:119], v[114:115]
	v_pk_mul_f32 v[120:121], v[120:121], v[116:117]
	v_cvt_pk_bf16_f32 v138, v118, v119
	v_cvt_pk_bf16_f32 v139, v120, v121
	global_store_dwordx4 v245, v[136:139], s[0:1] sc1
	v_pk_mul_f32 v[110:111], v[110:111], v[106:107]
	v_pk_mul_f32 v[112:113], v[112:113], v[108:109]
	v_cvt_pk_bf16_f32 v140, v110, v111
	v_cvt_pk_bf16_f32 v141, v112, v113
	v_pk_mul_f32 v[102:103], v[102:103], v[98:99]
	v_pk_mul_f32 v[104:105], v[104:105], v[100:101]
	v_cvt_pk_bf16_f32 v142, v102, v103
	v_cvt_pk_bf16_f32 v143, v104, v105
	v_add_u32_e32 v246, 0x10800, v245
	global_store_dwordx4 v246, v[140:143], s[0:1] sc1
	v_pk_mul_f32 v[94:95], v[94:95], v[90:91]
	v_pk_mul_f32 v[96:97], v[96:97], v[92:93]
	v_cvt_pk_bf16_f32 v158, v94, v95
	v_cvt_pk_bf16_f32 v159, v96, v97
	v_pk_mul_f32 v[86:87], v[86:87], v[82:83]
	v_pk_mul_f32 v[88:89], v[88:89], v[84:85]
	v_cvt_pk_bf16_f32 v160, v86, v87
	v_cvt_pk_bf16_f32 v161, v88, v89
	v_add_u32_e32 v255, 0x21000, v245
	global_store_dwordx4 v255, v[158:161], s[0:1] sc1
	v_pk_mul_f32 v[78:79], v[78:79], v[74:75]
	v_pk_mul_f32 v[80:81], v[80:81], v[76:77]
	v_cvt_pk_bf16_f32 v162, v78, v79
	v_cvt_pk_bf16_f32 v163, v80, v81
	v_pk_mul_f32 v[70:71], v[70:71], v[66:67]
	v_pk_mul_f32 v[72:73], v[72:73], v[68:69]
	v_cvt_pk_bf16_f32 v164, v70, v71
	v_cvt_pk_bf16_f32 v165, v72, v73
	v_add_u32_e32 v246, 0x31800, v245
	global_store_dwordx4 v246, v[162:165], s[0:1] sc1
	v_pk_mul_f32 v[62:63], v[62:63], v[58:59]
	v_pk_mul_f32 v[64:65], v[64:65], v[60:61]
	v_cvt_pk_bf16_f32 v166, v62, v63
	v_cvt_pk_bf16_f32 v167, v64, v65
	v_pk_mul_f32 v[54:55], v[54:55], v[50:51]
	v_pk_mul_f32 v[56:57], v[56:57], v[52:53]
	v_cvt_pk_bf16_f32 v168, v54, v55
	v_cvt_pk_bf16_f32 v169, v56, v57
	v_add_u32_e32 v255, 0x84000, v245
	global_store_dwordx4 v255, v[166:169], s[0:1] sc1
	v_pk_mul_f32 v[46:47], v[46:47], v[42:43]
	v_pk_mul_f32 v[48:49], v[48:49], v[44:45]
	v_cvt_pk_bf16_f32 v170, v46, v47
	v_cvt_pk_bf16_f32 v171, v48, v49
	v_pk_mul_f32 v[38:39], v[38:39], v[34:35]
	v_pk_mul_f32 v[40:41], v[40:41], v[36:37]
	v_cvt_pk_bf16_f32 v172, v38, v39
	v_cvt_pk_bf16_f32 v173, v40, v41
	v_add_u32_e32 v246, 0x94800, v245
	global_store_dwordx4 v246, v[170:173], s[0:1] sc1
	v_pk_mul_f32 v[30:31], v[30:31], v[26:27]
	v_pk_mul_f32 v[32:33], v[32:33], v[28:29]
	v_cvt_pk_bf16_f32 v174, v30, v31
	v_cvt_pk_bf16_f32 v175, v32, v33
	v_pk_mul_f32 v[22:23], v[22:23], v[18:19]
	v_pk_mul_f32 v[24:25], v[24:25], v[20:21]
	v_cvt_pk_bf16_f32 v176, v22, v23
	v_cvt_pk_bf16_f32 v177, v24, v25
	v_add_u32_e32 v255, 0xa5000, v245
	global_store_dwordx4 v255, v[174:177], s[0:1] sc1
	v_pk_mul_f32 v[14:15], v[14:15], v[10:11]
	v_pk_mul_f32 v[16:17], v[16:17], v[12:13]
	v_cvt_pk_bf16_f32 v178, v14, v15
	v_cvt_pk_bf16_f32 v179, v16, v17
	v_pk_mul_f32 v[6:7], v[6:7], v[2:3]
	v_pk_mul_f32 v[8:9], v[8:9], v[4:5]
	v_cvt_pk_bf16_f32 v180, v6, v7
	v_cvt_pk_bf16_f32 v181, v8, v9
	v_add_u32_e32 v246, 0xb5800, v245
	global_store_dwordx4 v246, v[178:181], s[0:1] sc1
	s_branch .Lmy_p1b_done
; __device__ __forceinline__ unsigned cvt_pk_bf16(float lo, float hi) { unsigned r; asm volatile("v_cvt_pk_bf16_f32 %0, %1, %2" : "=v"(r) : "v"(lo), "v"(hi)); return r; }
;     __device__ __forceinline__ void operator()(EPI_ARGS) const {
;     ...
;             bf16* base = BG + (size_t)((pn - 32) * BM + c8);
; #pragma unroll
;             for (int ai = 0; ai < 2; ++ai)
; #pragma unroll
;                 for (int m = 0; m < 4; ++m)
; #pragma unroll
;                     for (int bj = 0; bj < 2; ++bj) { const f32x4 v0 = acc[ai][bj][m][0], v1 = acc[ai][bj][m][1];
;                         u32x4 w; w.x = cvt_pk_bf16(v0[0], v0[1]); w.y = cvt_pk_bf16(v0[2], v0[3]); w.z = cvt_pk_bf16(v1[0], v1[1]); w.w = cvt_pk_bf16(v1[2], v1[3]);
;                         *(u32x4*)(base + (size_t)(row0 + ai * HALF + m * 16) * CWID + bj * HALF) = w; }
.Lmy_p1b_bg:
	s_sub_i32 s0, s91, 16
	s_lshl_b32 s0, s0, 9
	v_add_u32_e32 v245, s0, v245
	v_readlane_b32 s0, v244, 49
	v_readlane_b32 s1, v244, 50
	s_nop 4
	v_cvt_pk_bf16_f32 v136, v126, v127
	v_cvt_pk_bf16_f32 v137, v128, v129
	v_cvt_pk_bf16_f32 v138, v118, v119
	v_cvt_pk_bf16_f32 v139, v120, v121
	global_store_dwordx4 v245, v[136:139], s[0:1] sc1
	v_cvt_pk_bf16_f32 v140, v122, v123
	v_cvt_pk_bf16_f32 v141, v124, v125
	v_cvt_pk_bf16_f32 v142, v114, v115
	v_cvt_pk_bf16_f32 v143, v116, v117
	global_store_dwordx4 v245, v[140:143], s[0:1] offset:256 sc1
	v_add_u32_e32 v246, 0x10800, v245
	v_cvt_pk_bf16_f32 v158, v110, v111
	v_cvt_pk_bf16_f32 v159, v112, v113
	v_cvt_pk_bf16_f32 v160, v102, v103
	v_cvt_pk_bf16_f32 v161, v104, v105
	global_store_dwordx4 v246, v[158:161], s[0:1] sc1
	v_cvt_pk_bf16_f32 v162, v106, v107
	v_cvt_pk_bf16_f32 v163, v108, v109
	v_cvt_pk_bf16_f32 v164, v98, v99
	v_cvt_pk_bf16_f32 v165, v100, v101
	global_store_dwordx4 v246, v[162:165], s[0:1] offset:256 sc1
	v_add_u32_e32 v255, 0x21000, v245
	v_cvt_pk_bf16_f32 v166, v94, v95
	v_cvt_pk_bf16_f32 v167, v96, v97
	v_cvt_pk_bf16_f32 v168, v86, v87
	v_cvt_pk_bf16_f32 v169, v88, v89
	global_store_dwordx4 v255, v[166:169], s[0:1] sc1
	v_cvt_pk_bf16_f32 v170, v90, v91
	v_cvt_pk_bf16_f32 v171, v92, v93
	v_cvt_pk_bf16_f32 v172, v82, v83
	v_cvt_pk_bf16_f32 v173, v84, v85
	global_store_dwordx4 v255, v[170:173], s[0:1] offset:256 sc1
	v_add_u32_e32 v246, 0x31800, v245
	v_cvt_pk_bf16_f32 v174, v78, v79
	v_cvt_pk_bf16_f32 v175, v80, v81
	v_cvt_pk_bf16_f32 v176, v70, v71
	v_cvt_pk_bf16_f32 v177, v72, v73
	global_store_dwordx4 v246, v[174:177], s[0:1] sc1
	v_cvt_pk_bf16_f32 v178, v74, v75
	v_cvt_pk_bf16_f32 v179, v76, v77
	v_cvt_pk_bf16_f32 v180, v66, v67
	v_cvt_pk_bf16_f32 v181, v68, v69
	global_store_dwordx4 v246, v[178:181], s[0:1] offset:256 sc1
	v_add_u32_e32 v255, 0x84000, v245
	v_cvt_pk_bf16_f32 v182, v62, v63
	v_cvt_pk_bf16_f32 v183, v64, v65
	v_cvt_pk_bf16_f32 v184, v54, v55
	v_cvt_pk_bf16_f32 v185, v56, v57
	global_store_dwordx4 v255, v[182:185], s[0:1] sc1
	v_cvt_pk_bf16_f32 v186, v58, v59
	v_cvt_pk_bf16_f32 v187, v60, v61
	v_cvt_pk_bf16_f32 v188, v50, v51
	v_cvt_pk_bf16_f32 v189, v52, v53
	global_store_dwordx4 v255, v[186:189], s[0:1] offset:256 sc1
	v_add_u32_e32 v246, 0x94800, v245
	v_cvt_pk_bf16_f32 v190, v46, v47
	v_cvt_pk_bf16_f32 v191, v48, v49
	v_cvt_pk_bf16_f32 v192, v38, v39
	v_cvt_pk_bf16_f32 v193, v40, v41
	global_store_dwordx4 v246, v[190:193], s[0:1] sc1
	v_cvt_pk_bf16_f32 v194, v42, v43
	v_cvt_pk_bf16_f32 v195, v44, v45
	v_cvt_pk_bf16_f32 v196, v34, v35
	v_cvt_pk_bf16_f32 v197, v36, v37
	global_store_dwordx4 v246, v[194:197], s[0:1] offset:256 sc1
	v_add_u32_e32 v255, 0xa5000, v245
	v_cvt_pk_bf16_f32 v198, v30, v31
	v_cvt_pk_bf16_f32 v199, v32, v33
	v_cvt_pk_bf16_f32 v200, v22, v23
	v_cvt_pk_bf16_f32 v201, v24, v25
	global_store_dwordx4 v255, v[198:201], s[0:1] sc1
	v_cvt_pk_bf16_f32 v202, v26, v27
	v_cvt_pk_bf16_f32 v203, v28, v29
	v_cvt_pk_bf16_f32 v204, v18, v19
	v_cvt_pk_bf16_f32 v205, v20, v21
	global_store_dwordx4 v255, v[202:205], s[0:1] offset:256 sc1
	v_add_u32_e32 v246, 0xb5800, v245
	v_cvt_pk_bf16_f32 v206, v14, v15
	v_cvt_pk_bf16_f32 v207, v16, v17
	v_cvt_pk_bf16_f32 v208, v6, v7
	v_cvt_pk_bf16_f32 v209, v8, v9
	global_store_dwordx4 v246, v[206:209], s[0:1] sc1
	v_cvt_pk_bf16_f32 v210, v10, v11
	v_cvt_pk_bf16_f32 v211, v12, v13
	v_cvt_pk_bf16_f32 v212, v2, v3
	v_cvt_pk_bf16_f32 v213, v4, v5
	global_store_dwordx4 v246, v[210:213], s[0:1] offset:256 sc1

; __device__ __forceinline__ unsigned cvt_pk_bf16(float lo, float hi) { unsigned r; asm volatile("v_cvt_pk_bf16_f32 %0, %1, %2" : "=v"(r) : "v"(lo), "v"(hi)); return r; }
; __device__ __forceinline__ float bf_lo(unsigned w) { return __uint_as_float(w << 16); }
;     __device__ __forceinline__ void operator()(EPI_ARGS) const {
;     ...
;                 for (int bj = 0; bj < 2; ++bj) { const size_t off = (size_t)(row0 + ai * HALF + m * 16) * ldc + col0 + bj * HALF;
;                     if (RES_BF16) { const u32x4 rw = *(const u32x4*)((const bf16*)resid + off); r0[m][bj] = __builtin_bit_cast(f32x4, rw); }
;                     else { r0[m][bj] = *(const f32x4*)((const float*)resid + off); r1[m][bj] = *(const f32x4*)((const float*)resid + off + 4); } }
; #pragma unroll
;             for (int m = 0; m < 4; ++m) { const int row = row0 + ai * HALF + m * 16; const size_t off = (size_t)row * ldc + col0; float ss = 0.f, mx = 0.f;
; #pragma unroll
;                 for (int bj = 0; bj < 2; ++bj) {
;                     f32x4 a0, a1;
;                     if (RES_BF16) { const u32x4 rw = __builtin_bit_cast(u32x4, r0[m][bj]); a0 = (f32x4){bf_lo(rw.x), bf_hi(rw.x), bf_lo(rw.y), bf_hi(rw.y)}; a1 = (f32x4){bf_lo(rw.z), bf_hi(rw.z), bf_lo(rw.w), bf_hi(rw.w)};
;                         if (RES_SCALE) { const float rf = rfac[row]; a0 = a0 * rf; a1 = a1 * rf; } }
;                     else { a0 = r0[m][bj]; a1 = r1[m][bj]; }
;                     const f32x4 v0 = acc[ai][bj][m][0] + a0, v1 = acc[ai][bj][m][1] + a1;
;                     u32x4 w; w.x = cvt_pk_bf16(v0[0], v0[1]); w.y = cvt_pk_bf16(v0[2], v0[3]); w.z = cvt_pk_bf16(v1[0], v1[1]); w.w = cvt_pk_bf16(v1[2], v1[3]); *(u32x4*)(ob + off + bj * HALF) = w;
;                     ss += (v0[0] * v0[0] + v0[1] * v0[1]) + (v0[2] * v0[2] + v0[3] * v0[3]) + (v1[0] * v1[0] + v1[1] * v1[1]) + (v1[2] * v1[2] + v1[3] * v1[3]);
;                     if (rowmax) mx = fmaxf(mx, fmaxf(fmaxf(fmaxf(fabsf(v0[0]), fabsf(v0[1])), fmaxf(fabsf(v0[2]), fabsf(v0[3]))), fmaxf(fmaxf(fabsf(v1[0]), fabsf(v1[1])), fmaxf(fabsf(v1[2]), fabsf(v1[3]))))); }
;                 ss += __shfl_xor(ss, 16); ss += __shfl_xor(ss, 32); ssv[ai * 4 + m] = ss;
;                 if (rowmax) { mx = fmaxf(mx, __shfl_xor(mx, 16)); mx = fmaxf(mx, __shfl_xor(mx, 32)); } mxv[ai * 4 + m] = mx; }
.LBB0_1005:
	s_nop 7
	v_lshl_add_u32 v245, s72, 8, v181
	v_lshlrev_b32_e32 v245, 13, v245
	v_lshl_or_b32 v246, s70, 8, v182
	v_lshl_add_u32 v245, v246, 1, v245
	global_load_dwordx4 v[130:133], v245, s[52:53]
	global_load_dwordx4 v[134:137], v245, s[52:53] offset:256
	v_add_u32_e32 v246, 0x20000, v245
	global_load_dwordx4 v[138:141], v246, s[52:53]
	global_load_dwordx4 v[142:145], v246, s[52:53] offset:256
	v_add_u32_e32 v255, 0x40000, v245
	global_load_dwordx4 v[146:149], v255, s[52:53]
	global_load_dwordx4 v[150:153], v255, s[52:53] offset:256
	v_add_u32_e32 v246, 0x60000, v245
	global_load_dwordx4 v[154:157], v246, s[52:53]
	global_load_dwordx4 v[162:165], v246, s[52:53] offset:256
	v_add_u32_e32 v255, 0x100000, v245
	global_load_dwordx4 v[166:169], v255, s[52:53]
	global_load_dwordx4 v[170:173], v255, s[52:53] offset:256
	v_add_u32_e32 v246, 0x120000, v245
	global_load_dwordx4 v[190:193], v246, s[52:53]
	global_load_dwordx4 v[194:197], v246, s[52:53] offset:256
	v_add_u32_e32 v255, 0x140000, v245
	global_load_dwordx4 v[198:201], v255, s[52:53]
	global_load_dwordx4 v[202:205], v255, s[52:53] offset:256
	v_add_u32_e32 v246, 0x160000, v245
	global_load_dwordx4 v[206:209], v246, s[52:53]
	global_load_dwordx4 v[210:213], v246, s[52:53] offset:256
	v_lshl_add_u32 v245, s72, 8, v181
	v_mul_u32_u24_e32 v245, 0x2080, v245
	v_lshl_or_b32 v246, s70, 8, v182
	v_lshl_add_u32 v245, v246, 1, v245
	s_waitcnt vmcnt(15)
	v_lshlrev_b32_e32 v248, 16, v130
	v_and_b32_e32 v249, 0xffff0000, v130
	v_lshlrev_b32_e32 v250, 16, v131
	v_and_b32_e32 v251, 0xffff0000, v131
	v_pk_add_f32 v[126:127], v[126:127], v[248:249]
	v_pk_add_f32 v[128:129], v[128:129], v[250:251]
	v_lshlrev_b32_e32 v248, 16, v132
	v_and_b32_e32 v249, 0xffff0000, v132
	v_lshlrev_b32_e32 v250, 16, v133
	v_and_b32_e32 v251, 0xffff0000, v133
	v_pk_add_f32 v[122:123], v[122:123], v[248:249]
	v_pk_add_f32 v[124:125], v[124:125], v[250:251]
	v_cvt_pk_bf16_f32 v130, v126, v127
	v_cvt_pk_bf16_f32 v131, v128, v129
	v_cvt_pk_bf16_f32 v132, v122, v123
	v_cvt_pk_bf16_f32 v133, v124, v125
	global_store_dwordx4 v245, v[130:133], s[100:101] sc1
	v_mul_f32_e32 v247, v126, v126
	v_fmac_f32_e32 v247, v127, v127
	v_fmac_f32_e32 v247, v128, v128
	v_fmac_f32_e32 v247, v129, v129
	v_mul_f32_e32 v254, v122, v122
	v_fmac_f32_e32 v254, v123, v123
	v_fmac_f32_e32 v254, v124, v124
	v_fmac_f32_e32 v254, v125, v125
	v_max3_f32 v252, |v126|, |v127|, |v128|
	v_max3_f32 v252, |v129|, |v122|, v252
	v_max3_f32 v252, |v123|, |v124|, v252
	v_max_f32_e64 v252, |v125|, v252
	s_waitcnt vmcnt(15)
	v_lshlrev_b32_e32 v248, 16, v134
	v_and_b32_e32 v249, 0xffff0000, v134
	v_lshlrev_b32_e32 v250, 16, v135
	v_and_b32_e32 v251, 0xffff0000, v135
	v_pk_add_f32 v[118:119], v[118:119], v[248:249]
	v_pk_add_f32 v[120:121], v[120:121], v[250:251]
	v_lshlrev_b32_e32 v248, 16, v136
	v_and_b32_e32 v249, 0xffff0000, v136
	v_lshlrev_b32_e32 v250, 16, v137
	v_and_b32_e32 v251, 0xffff0000, v137
	v_pk_add_f32 v[114:115], v[114:115], v[248:249]
	v_pk_add_f32 v[116:117], v[116:117], v[250:251]
	v_cvt_pk_bf16_f32 v134, v118, v119
	v_cvt_pk_bf16_f32 v135, v120, v121
	v_cvt_pk_bf16_f32 v136, v114, v115
	v_cvt_pk_bf16_f32 v137, v116, v117
	global_store_dwordx4 v245, v[134:137], s[100:101] offset:256 sc1
	v_fmac_f32_e32 v247, v118, v118
	v_fmac_f32_e32 v247, v119, v119
	v_fmac_f32_e32 v247, v120, v120
	v_fmac_f32_e32 v247, v121, v121
	v_fmac_f32_e32 v254, v114, v114
	v_fmac_f32_e32 v254, v115, v115
	v_fmac_f32_e32 v254, v116, v116
	v_fmac_f32_e32 v254, v117, v117
	v_max3_f32 v252, |v118|, |v119|, v252
	v_max_f32_e64 v252, |v120|, v252
	v_max3_f32 v252, |v121|, |v114|, v252
	v_max3_f32 v252, |v115|, |v116|, v252
	v_max_f32_e64 v252, |v117|, v252
	v_add_f32_e32 v126, v247, v254
	v_mov_b32_e32 v128, v252
	s_waitcnt vmcnt(15)
	v_lshlrev_b32_e32 v248, 16, v138
	v_and_b32_e32 v249, 0xffff0000, v138
	v_lshlrev_b32_e32 v250, 16, v139
	v_and_b32_e32 v251, 0xffff0000, v139
	v_pk_add_f32 v[110:111], v[110:111], v[248:249]
	v_pk_add_f32 v[112:113], v[112:113], v[250:251]
	v_lshlrev_b32_e32 v248, 16, v140
	v_and_b32_e32 v249, 0xffff0000, v140
	v_lshlrev_b32_e32 v250, 16, v141
	v_and_b32_e32 v251, 0xffff0000, v141
	v_pk_add_f32 v[106:107], v[106:107], v[248:249]
	v_pk_add_f32 v[108:109], v[108:109], v[250:251]
	v_cvt_pk_bf16_f32 v138, v110, v111
	v_cvt_pk_bf16_f32 v139, v112, v113
	v_cvt_pk_bf16_f32 v140, v106, v107
	v_cvt_pk_bf16_f32 v141, v108, v109
	v_add_u32_e32 v246, 0x20800, v245
	global_store_dwordx4 v246, v[138:141], s[100:101] sc1
	v_mul_f32_e32 v247, v110, v110
	v_fmac_f32_e32 v247, v111, v111
	v_fmac_f32_e32 v247, v112, v112
	v_fmac_f32_e32 v247, v113, v113
	v_mul_f32_e32 v254, v106, v106
	v_fmac_f32_e32 v254, v107, v107
	v_fmac_f32_e32 v254, v108, v108
	v_fmac_f32_e32 v254, v109, v109
	v_max3_f32 v252, |v110|, |v111|, |v112|
	v_max3_f32 v252, |v113|, |v106|, v252
	v_max3_f32 v252, |v107|, |v108|, v252
	v_max_f32_e64 v252, |v109|, v252
	s_waitcnt vmcnt(15)
	v_lshlrev_b32_e32 v248, 16, v142
	v_and_b32_e32 v249, 0xffff0000, v142
	v_lshlrev_b32_e32 v250, 16, v143
	v_and_b32_e32 v251, 0xffff0000, v143
	v_pk_add_f32 v[102:103], v[102:103], v[248:249]
	v_pk_add_f32 v[104:105], v[104:105], v[250:251]
	v_lshlrev_b32_e32 v248, 16, v144
	v_and_b32_e32 v249, 0xffff0000, v144
	v_lshlrev_b32_e32 v250, 16, v145
	v_and_b32_e32 v251, 0xffff0000, v145
	v_pk_add_f32 v[98:99], v[98:99], v[248:249]
	v_pk_add_f32 v[100:101], v[100:101], v[250:251]
	v_cvt_pk_bf16_f32 v142, v102, v103
	v_cvt_pk_bf16_f32 v143, v104, v105
	v_cvt_pk_bf16_f32 v144, v98, v99
	v_cvt_pk_bf16_f32 v145, v100, v101
	v_add_u32_e32 v255, 0x20800, v245
	global_store_dwordx4 v255, v[142:145], s[100:101] offset:256 sc1
	v_fmac_f32_e32 v247, v102, v102
	v_fmac_f32_e32 v247, v103, v103
	v_fmac_f32_e32 v247, v104, v104
	v_fmac_f32_e32 v247, v105, v105
	v_fmac_f32_e32 v254, v98, v98
	v_fmac_f32_e32 v254, v99, v99
	v_fmac_f32_e32 v254, v100, v100
	v_fmac_f32_e32 v254, v101, v101
	v_max3_f32 v252, |v102|, |v103|, v252
	v_max_f32_e64 v252, |v104|, v252
	v_max3_f32 v252, |v105|, |v98|, v252
	v_max3_f32 v252, |v99|, |v100|, v252
	v_max_f32_e64 v252, |v101|, v252
	v_add_f32_e32 v110, v247, v254
	v_mov_b32_e32 v112, v252
	s_waitcnt vmcnt(15)
; __device__ __forceinline__ unsigned cvt_pk_bf16(float lo, float hi) { unsigned r; asm volatile("v_cvt_pk_bf16_f32 %0, %1, %2" : "=v"(r) : "v"(lo), "v"(hi)); return r; }
; __device__ __forceinline__ float bf_lo(unsigned w) { return __uint_as_float(w << 16); }
; __device__ __forceinline__ float bf_hi(unsigned w) { return __uint_as_float(w & 0xffff0000u); }
;     __device__ __forceinline__ void operator()(EPI_ARGS) const {
;     ...
;             for (int m = 0; m < 4; ++m) { const int row = row0 + ai * HALF + m * 16; const size_t off = (size_t)row * ldc + col0; float ss = 0.f, mx = 0.f;
; #pragma unroll
;                 for (int bj = 0; bj < 2; ++bj) {
;                     f32x4 a0, a1;
;                     if (RES_BF16) { const u32x4 rw = __builtin_bit_cast(u32x4, r0[m][bj]); a0 = (f32x4){bf_lo(rw.x), bf_hi(rw.x), bf_lo(rw.y), bf_hi(rw.y)}; a1 = (f32x4){bf_lo(rw.z), bf_hi(rw.z), bf_lo(rw.w), bf_hi(rw.w)};
;                         if (RES_SCALE) { const float rf = rfac[row]; a0 = a0 * rf; a1 = a1 * rf; } }
;                     else { a0 = r0[m][bj]; a1 = r1[m][bj]; }
;                     const f32x4 v0 = acc[ai][bj][m][0] + a0, v1 = acc[ai][bj][m][1] + a1;
;                     u32x4 w; w.x = cvt_pk_bf16(v0[0], v0[1]); w.y = cvt_pk_bf16(v0[2], v0[3]); w.z = cvt_pk_bf16(v1[0], v1[1]); w.w = cvt_pk_bf16(v1[2], v1[3]); *(u32x4*)(ob + off + bj * HALF) = w;
;                     ss += (v0[0] * v0[0] + v0[1] * v0[1]) + (v0[2] * v0[2] + v0[3] * v0[3]) + (v1[0] * v1[0] + v1[1] * v1[1]) + (v1[2] * v1[2] + v1[3] * v1[3]);
;                     if (rowmax) mx = fmaxf(mx, fmaxf(fmaxf(fmaxf(fabsf(v0[0]), fabsf(v0[1])), fmaxf(fabsf(v0[2]), fabsf(v0[3]))), fmaxf(fmaxf(fabsf(v1[0]), fabsf(v1[1])), fmaxf(fabsf(v1[2]), fabsf(v1[3]))))); }
;                 ss += __shfl_xor(ss, 16); ss += __shfl_xor(ss, 32); ssv[ai * 4 + m] = ss;
;                 if (rowmax) { mx = fmaxf(mx, __shfl_xor(mx, 16)); mx = fmaxf(mx, __shfl_xor(mx, 32)); } mxv[ai * 4 + m] = mx; }
	v_lshlrev_b32_e32 v248, 16, v146
	v_and_b32_e32 v249, 0xffff0000, v146
	v_lshlrev_b32_e32 v250, 16, v147
	v_and_b32_e32 v251, 0xffff0000, v147
	v_pk_add_f32 v[94:95], v[94:95], v[248:249]
	v_pk_add_f32 v[96:97], v[96:97], v[250:251]
	v_lshlrev_b32_e32 v248, 16, v148
	v_and_b32_e32 v249, 0xffff0000, v148
	v_lshlrev_b32_e32 v250, 16, v149
	v_and_b32_e32 v251, 0xffff0000, v149
	v_pk_add_f32 v[90:91], v[90:91], v[248:249]
	v_pk_add_f32 v[92:93], v[92:93], v[250:251]
	v_cvt_pk_bf16_f32 v146, v94, v95
	v_cvt_pk_bf16_f32 v147, v96, v97
	v_cvt_pk_bf16_f32 v148, v90, v91
	v_cvt_pk_bf16_f32 v149, v92, v93
	v_add_u32_e32 v246, 0x41000, v245
	global_store_dwordx4 v246, v[146:149], s[100:101] sc1
	v_mul_f32_e32 v247, v94, v94
	v_fmac_f32_e32 v247, v95, v95
	v_fmac_f32_e32 v247, v96, v96
	v_fmac_f32_e32 v247, v97, v97
	v_mul_f32_e32 v254, v90, v90
	v_fmac_f32_e32 v254, v91, v91
	v_fmac_f32_e32 v254, v92, v92
	v_fmac_f32_e32 v254, v93, v93
	v_max3_f32 v252, |v94|, |v95|, |v96|
	v_max3_f32 v252, |v97|, |v90|, v252
	v_max3_f32 v252, |v91|, |v92|, v252
	v_max_f32_e64 v252, |v93|, v252
	s_waitcnt vmcnt(15)
	v_lshlrev_b32_e32 v248, 16, v150
	v_and_b32_e32 v249, 0xffff0000, v150
	v_lshlrev_b32_e32 v250, 16, v151
	v_and_b32_e32 v251, 0xffff0000, v151
	v_pk_add_f32 v[86:87], v[86:87], v[248:249]
	v_pk_add_f32 v[88:89], v[88:89], v[250:251]
	v_lshlrev_b32_e32 v248, 16, v152
	v_and_b32_e32 v249, 0xffff0000, v152
	v_lshlrev_b32_e32 v250, 16, v153
	v_and_b32_e32 v251, 0xffff0000, v153
	v_pk_add_f32 v[82:83], v[82:83], v[248:249]
	v_pk_add_f32 v[84:85], v[84:85], v[250:251]
	v_cvt_pk_bf16_f32 v150, v86, v87
	v_cvt_pk_bf16_f32 v151, v88, v89
	v_cvt_pk_bf16_f32 v152, v82, v83
	v_cvt_pk_bf16_f32 v153, v84, v85
	v_add_u32_e32 v255, 0x41000, v245
	global_store_dwordx4 v255, v[150:153], s[100:101] offset:256 sc1
	v_fmac_f32_e32 v247, v86, v86
	v_fmac_f32_e32 v247, v87, v87
	v_fmac_f32_e32 v247, v88, v88
	v_fmac_f32_e32 v247, v89, v89
	v_fmac_f32_e32 v254, v82, v82
	v_fmac_f32_e32 v254, v83, v83
	v_fmac_f32_e32 v254, v84, v84
	v_fmac_f32_e32 v254, v85, v85
	v_max3_f32 v252, |v86|, |v87|, v252
	v_max_f32_e64 v252, |v88|, v252
	v_max3_f32 v252, |v89|, |v82|, v252
	v_max3_f32 v252, |v83|, |v84|, v252
	v_max_f32_e64 v252, |v85|, v252
	v_add_f32_e32 v94, v247, v254
	v_mov_b32_e32 v96, v252
	s_waitcnt vmcnt(15)
	v_lshlrev_b32_e32 v248, 16, v154
	v_and_b32_e32 v249, 0xffff0000, v154
	v_lshlrev_b32_e32 v250, 16, v155
	v_and_b32_e32 v251, 0xffff0000, v155
	v_pk_add_f32 v[78:79], v[78:79], v[248:249]
	v_pk_add_f32 v[80:81], v[80:81], v[250:251]
	v_lshlrev_b32_e32 v248, 16, v156
	v_and_b32_e32 v249, 0xffff0000, v156
	v_lshlrev_b32_e32 v250, 16, v157
	v_and_b32_e32 v251, 0xffff0000, v157
	v_pk_add_f32 v[74:75], v[74:75], v[248:249]
	v_pk_add_f32 v[76:77], v[76:77], v[250:251]
	v_cvt_pk_bf16_f32 v154, v78, v79
	v_cvt_pk_bf16_f32 v155, v80, v81
	v_cvt_pk_bf16_f32 v156, v74, v75
	v_cvt_pk_bf16_f32 v157, v76, v77
	v_add_u32_e32 v246, 0x61800, v245
	global_store_dwordx4 v246, v[154:157], s[100:101] sc1
	v_mul_f32_e32 v247, v78, v78
	v_fmac_f32_e32 v247, v79, v79
	v_fmac_f32_e32 v247, v80, v80
	v_fmac_f32_e32 v247, v81, v81
	v_mul_f32_e32 v254, v74, v74
	v_fmac_f32_e32 v254, v75, v75
	v_fmac_f32_e32 v254, v76, v76
	v_fmac_f32_e32 v254, v77, v77
	v_max3_f32 v252, |v78|, |v79|, |v80|
	v_max3_f32 v252, |v81|, |v74|, v252
	v_max3_f32 v252, |v75|, |v76|, v252
	v_max_f32_e64 v252, |v77|, v252
	s_waitcnt vmcnt(15)
	v_lshlrev_b32_e32 v248, 16, v162
	v_and_b32_e32 v249, 0xffff0000, v162
	v_lshlrev_b32_e32 v250, 16, v163
	v_and_b32_e32 v251, 0xffff0000, v163
	v_pk_add_f32 v[70:71], v[70:71], v[248:249]
	v_pk_add_f32 v[72:73], v[72:73], v[250:251]
	v_lshlrev_b32_e32 v248, 16, v164
	v_and_b32_e32 v249, 0xffff0000, v164
	v_lshlrev_b32_e32 v250, 16, v165
	v_and_b32_e32 v251, 0xffff0000, v165
	v_pk_add_f32 v[66:67], v[66:67], v[248:249]
	v_pk_add_f32 v[68:69], v[68:69], v[250:251]
	v_cvt_pk_bf16_f32 v162, v70, v71
	v_cvt_pk_bf16_f32 v163, v72, v73
	v_cvt_pk_bf16_f32 v164, v66, v67
	v_cvt_pk_bf16_f32 v165, v68, v69
	v_add_u32_e32 v255, 0x61800, v245
	global_store_dwordx4 v255, v[162:165], s[100:101] offset:256 sc1
	v_fmac_f32_e32 v247, v70, v70
	v_fmac_f32_e32 v247, v71, v71
	v_fmac_f32_e32 v247, v72, v72
	v_fmac_f32_e32 v247, v73, v73
	v_fmac_f32_e32 v254, v66, v66
	v_fmac_f32_e32 v254, v67, v67
	v_fmac_f32_e32 v254, v68, v68
	v_fmac_f32_e32 v254, v69, v69
	v_max3_f32 v252, |v70|, |v71|, v252
	v_max_f32_e64 v252, |v72|, v252
	v_max3_f32 v252, |v73|, |v66|, v252
	v_max3_f32 v252, |v67|, |v68|, v252
	v_max_f32_e64 v252, |v69|, v252
	v_add_f32_e32 v78, v247, v254
	v_mov_b32_e32 v80, v252
	s_waitcnt vmcnt(15)
	v_lshlrev_b32_e32 v248, 16, v166
	v_and_b32_e32 v249, 0xffff0000, v166
	v_lshlrev_b32_e32 v250, 16, v167
	v_and_b32_e32 v251, 0xffff0000, v167
	v_pk_add_f32 v[62:63], v[62:63], v[248:249]
	v_pk_add_f32 v[64:65], v[64:65], v[250:251]
	v_lshlrev_b32_e32 v248, 16, v168
	v_and_b32_e32 v249, 0xffff0000, v168
	v_lshlrev_b32_e32 v250, 16, v169
	v_and_b32_e32 v251, 0xffff0000, v169
	v_pk_add_f32 v[58:59], v[58:59], v[248:249]
	v_pk_add_f32 v[60:61], v[60:61], v[250:251]
	v_cvt_pk_bf16_f32 v166, v62, v63
	v_cvt_pk_bf16_f32 v167, v64, v65
	v_cvt_pk_bf16_f32 v168, v58, v59
	v_cvt_pk_bf16_f32 v169, v60, v61
	v_add_u32_e32 v246, 0x104000, v245
	global_store_dwordx4 v246, v[166:169], s[100:101] sc1
	v_mul_f32_e32 v247, v62, v62
	v_fmac_f32_e32 v247, v63, v63
	v_fmac_f32_e32 v247, v64, v64
	v_fmac_f32_e32 v247, v65, v65
	v_mul_f32_e32 v254, v58, v58
	v_fmac_f32_e32 v254, v59, v59
	v_fmac_f32_e32 v254, v60, v60
	v_fmac_f32_e32 v254, v61, v61
	v_max3_f32 v252, |v62|, |v63|, |v64|
	v_max3_f32 v252, |v65|, |v58|, v252
	v_max3_f32 v252, |v59|, |v60|, v252
	v_max_f32_e64 v252, |v61|, v252
	s_waitcnt vmcnt(15)
; __device__ __forceinline__ unsigned cvt_pk_bf16(float lo, float hi) { unsigned r; asm volatile("v_cvt_pk_bf16_f32 %0, %1, %2" : "=v"(r) : "v"(lo), "v"(hi)); return r; }
; __device__ __forceinline__ float bf_lo(unsigned w) { return __uint_as_float(w << 16); }
; __device__ __forceinline__ float bf_hi(unsigned w) { return __uint_as_float(w & 0xffff0000u); }
;     __device__ __forceinline__ void operator()(EPI_ARGS) const {
;     ...
;             for (int m = 0; m < 4; ++m) { const int row = row0 + ai * HALF + m * 16; const size_t off = (size_t)row * ldc + col0; float ss = 0.f, mx = 0.f;
; #pragma unroll
;                 for (int bj = 0; bj < 2; ++bj) {
;                     f32x4 a0, a1;
;                     if (RES_BF16) { const u32x4 rw = __builtin_bit_cast(u32x4, r0[m][bj]); a0 = (f32x4){bf_lo(rw.x), bf_hi(rw.x), bf_lo(rw.y), bf_hi(rw.y)}; a1 = (f32x4){bf_lo(rw.z), bf_hi(rw.z), bf_lo(rw.w), bf_hi(rw.w)};
;                         if (RES_SCALE) { const float rf = rfac[row]; a0 = a0 * rf; a1 = a1 * rf; } }
;                     else { a0 = r0[m][bj]; a1 = r1[m][bj]; }
;                     const f32x4 v0 = acc[ai][bj][m][0] + a0, v1 = acc[ai][bj][m][1] + a1;
;                     u32x4 w; w.x = cvt_pk_bf16(v0[0], v0[1]); w.y = cvt_pk_bf16(v0[2], v0[3]); w.z = cvt_pk_bf16(v1[0], v1[1]); w.w = cvt_pk_bf16(v1[2], v1[3]); *(u32x4*)(ob + off + bj * HALF) = w;
;                     ss += (v0[0] * v0[0] + v0[1] * v0[1]) + (v0[2] * v0[2] + v0[3] * v0[3]) + (v1[0] * v1[0] + v1[1] * v1[1]) + (v1[2] * v1[2] + v1[3] * v1[3]);
;                     if (rowmax) mx = fmaxf(mx, fmaxf(fmaxf(fmaxf(fabsf(v0[0]), fabsf(v0[1])), fmaxf(fabsf(v0[2]), fabsf(v0[3]))), fmaxf(fmaxf(fabsf(v1[0]), fabsf(v1[1])), fmaxf(fabsf(v1[2]), fabsf(v1[3]))))); }
	v_lshlrev_b32_e32 v248, 16, v170
	v_and_b32_e32 v249, 0xffff0000, v170
	v_lshlrev_b32_e32 v250, 16, v171
	v_and_b32_e32 v251, 0xffff0000, v171
	v_pk_add_f32 v[54:55], v[54:55], v[248:249]
	v_pk_add_f32 v[56:57], v[56:57], v[250:251]
	v_lshlrev_b32_e32 v248, 16, v172
	v_and_b32_e32 v249, 0xffff0000, v172
	v_lshlrev_b32_e32 v250, 16, v173
	v_and_b32_e32 v251, 0xffff0000, v173
	v_pk_add_f32 v[50:51], v[50:51], v[248:249]
	v_pk_add_f32 v[52:53], v[52:53], v[250:251]
	v_cvt_pk_bf16_f32 v170, v54, v55
	v_cvt_pk_bf16_f32 v171, v56, v57
	v_cvt_pk_bf16_f32 v172, v50, v51
	v_cvt_pk_bf16_f32 v173, v52, v53
	v_add_u32_e32 v255, 0x104000, v245
	global_store_dwordx4 v255, v[170:173], s[100:101] offset:256 sc1
	v_fmac_f32_e32 v247, v54, v54
	v_fmac_f32_e32 v247, v55, v55
	v_fmac_f32_e32 v247, v56, v56
	v_fmac_f32_e32 v247, v57, v57
	v_fmac_f32_e32 v254, v50, v50
	v_fmac_f32_e32 v254, v51, v51
	v_fmac_f32_e32 v254, v52, v52
	v_fmac_f32_e32 v254, v53, v53
	v_max3_f32 v252, |v54|, |v55|, v252
	v_max_f32_e64 v252, |v56|, v252
	v_max3_f32 v252, |v57|, |v50|, v252
	v_max3_f32 v252, |v51|, |v52|, v252
	v_max_f32_e64 v252, |v53|, v252
	v_add_f32_e32 v62, v247, v254
	v_mov_b32_e32 v64, v252
	s_waitcnt vmcnt(15)
	v_lshlrev_b32_e32 v248, 16, v190
	v_and_b32_e32 v249, 0xffff0000, v190
	v_lshlrev_b32_e32 v250, 16, v191
	v_and_b32_e32 v251, 0xffff0000, v191
	v_pk_add_f32 v[46:47], v[46:47], v[248:249]
	v_pk_add_f32 v[48:49], v[48:49], v[250:251]
	v_lshlrev_b32_e32 v248, 16, v192
	v_and_b32_e32 v249, 0xffff0000, v192
	v_lshlrev_b32_e32 v250, 16, v193
	v_and_b32_e32 v251, 0xffff0000, v193
	v_pk_add_f32 v[42:43], v[42:43], v[248:249]
	v_pk_add_f32 v[44:45], v[44:45], v[250:251]
	v_cvt_pk_bf16_f32 v190, v46, v47
	v_cvt_pk_bf16_f32 v191, v48, v49
	v_cvt_pk_bf16_f32 v192, v42, v43
	v_cvt_pk_bf16_f32 v193, v44, v45
	v_add_u32_e32 v246, 0x124800, v245
	global_store_dwordx4 v246, v[190:193], s[100:101] sc1
	v_mul_f32_e32 v247, v46, v46
	v_fmac_f32_e32 v247, v47, v47
	v_fmac_f32_e32 v247, v48, v48
	v_fmac_f32_e32 v247, v49, v49
	v_mul_f32_e32 v254, v42, v42
	v_fmac_f32_e32 v254, v43, v43
	v_fmac_f32_e32 v254, v44, v44
	v_fmac_f32_e32 v254, v45, v45
	v_max3_f32 v252, |v46|, |v47|, |v48|
	v_max3_f32 v252, |v49|, |v42|, v252
	v_max3_f32 v252, |v43|, |v44|, v252
	v_max_f32_e64 v252, |v45|, v252
	s_waitcnt vmcnt(15)
	v_lshlrev_b32_e32 v248, 16, v194
	v_and_b32_e32 v249, 0xffff0000, v194
	v_lshlrev_b32_e32 v250, 16, v195
	v_and_b32_e32 v251, 0xffff0000, v195
	v_pk_add_f32 v[38:39], v[38:39], v[248:249]
	v_pk_add_f32 v[40:41], v[40:41], v[250:251]
	v_lshlrev_b32_e32 v248, 16, v196
	v_and_b32_e32 v249, 0xffff0000, v196
	v_lshlrev_b32_e32 v250, 16, v197
	v_and_b32_e32 v251, 0xffff0000, v197
	v_pk_add_f32 v[34:35], v[34:35], v[248:249]
	v_pk_add_f32 v[36:37], v[36:37], v[250:251]
	v_cvt_pk_bf16_f32 v194, v38, v39
	v_cvt_pk_bf16_f32 v195, v40, v41
	v_cvt_pk_bf16_f32 v196, v34, v35
	v_cvt_pk_bf16_f32 v197, v36, v37
	v_add_u32_e32 v255, 0x124800, v245
	global_store_dwordx4 v255, v[194:197], s[100:101] offset:256 sc1
	v_fmac_f32_e32 v247, v38, v38
	v_fmac_f32_e32 v247, v39, v39
	v_fmac_f32_e32 v247, v40, v40
	v_fmac_f32_e32 v247, v41, v41
	v_fmac_f32_e32 v254, v34, v34
	v_fmac_f32_e32 v254, v35, v35
	v_fmac_f32_e32 v254, v36, v36
	v_fmac_f32_e32 v254, v37, v37
	v_max3_f32 v252, |v38|, |v39|, v252
	v_max_f32_e64 v252, |v40|, v252
	v_max3_f32 v252, |v41|, |v34|, v252
	v_max3_f32 v252, |v35|, |v36|, v252
	v_max_f32_e64 v252, |v37|, v252
	v_add_f32_e32 v46, v247, v254
	v_mov_b32_e32 v48, v252
	s_waitcnt vmcnt(15)
	v_lshlrev_b32_e32 v248, 16, v198
	v_and_b32_e32 v249, 0xffff0000, v198
	v_lshlrev_b32_e32 v250, 16, v199
	v_and_b32_e32 v251, 0xffff0000, v199
	v_pk_add_f32 v[30:31], v[30:31], v[248:249]
	v_pk_add_f32 v[32:33], v[32:33], v[250:251]
	v_lshlrev_b32_e32 v248, 16, v200
	v_and_b32_e32 v249, 0xffff0000, v200
	v_lshlrev_b32_e32 v250, 16, v201
	v_and_b32_e32 v251, 0xffff0000, v201
	v_pk_add_f32 v[26:27], v[26:27], v[248:249]
	v_pk_add_f32 v[28:29], v[28:29], v[250:251]
	v_cvt_pk_bf16_f32 v198, v30, v31
	v_cvt_pk_bf16_f32 v199, v32, v33
	v_cvt_pk_bf16_f32 v200, v26, v27
	v_cvt_pk_bf16_f32 v201, v28, v29
	v_add_u32_e32 v246, 0x145000, v245
	global_store_dwordx4 v246, v[198:201], s[100:101] sc1
	v_mul_f32_e32 v247, v30, v30
	v_fmac_f32_e32 v247, v31, v31
	v_fmac_f32_e32 v247, v32, v32
	v_fmac_f32_e32 v247, v33, v33
	v_mul_f32_e32 v254, v26, v26
	v_fmac_f32_e32 v254, v27, v27
	v_fmac_f32_e32 v254, v28, v28
	v_fmac_f32_e32 v254, v29, v29
	v_max3_f32 v252, |v30|, |v31|, |v32|
	v_max3_f32 v252, |v33|, |v26|, v252
	v_max3_f32 v252, |v27|, |v28|, v252
	v_max_f32_e64 v252, |v29|, v252
	s_waitcnt vmcnt(15)
	v_lshlrev_b32_e32 v248, 16, v202
	v_and_b32_e32 v249, 0xffff0000, v202
	v_lshlrev_b32_e32 v250, 16, v203
	v_and_b32_e32 v251, 0xffff0000, v203
	v_pk_add_f32 v[22:23], v[22:23], v[248:249]
	v_pk_add_f32 v[24:25], v[24:25], v[250:251]
	v_lshlrev_b32_e32 v248, 16, v204
	v_and_b32_e32 v249, 0xffff0000, v204
	v_lshlrev_b32_e32 v250, 16, v205
	v_and_b32_e32 v251, 0xffff0000, v205
	v_pk_add_f32 v[18:19], v[18:19], v[248:249]
	v_pk_add_f32 v[20:21], v[20:21], v[250:251]
	v_cvt_pk_bf16_f32 v202, v22, v23
	v_cvt_pk_bf16_f32 v203, v24, v25
	v_cvt_pk_bf16_f32 v204, v18, v19
	v_cvt_pk_bf16_f32 v205, v20, v21
	v_add_u32_e32 v255, 0x145000, v245
	global_store_dwordx4 v255, v[202:205], s[100:101] offset:256 sc1
	v_fmac_f32_e32 v247, v22, v22
	v_fmac_f32_e32 v247, v23, v23
	v_fmac_f32_e32 v247, v24, v24
	v_fmac_f32_e32 v247, v25, v25
	v_fmac_f32_e32 v254, v18, v18
	v_fmac_f32_e32 v254, v19, v19
	v_fmac_f32_e32 v254, v20, v20
	v_fmac_f32_e32 v254, v21, v21
	v_max3_f32 v252, |v22|, |v23|, v252
	v_max_f32_e64 v252, |v24|, v252
	v_max3_f32 v252, |v25|, |v18|, v252
	v_max3_f32 v252, |v19|, |v20|, v252
	v_max_f32_e64 v252, |v21|, v252
	v_add_f32_e32 v30, v247, v254
	v_mov_b32_e32 v32, v252
	s_waitcnt vmcnt(15)
;     __device__ __forceinline__ void operator()(EPI_ARGS) const {
;     ...
;             for (int m = 0; m < 4; ++m) { const int row = row0 + ai * HALF + m * 16; const size_t off = (size_t)row * ldc + col0; float ss = 0.f, mx = 0.f;
; #pragma unroll
;                 for (int bj = 0; bj < 2; ++bj) {
;                     f32x4 a0, a1;
;                     if (RES_BF16) { const u32x4 rw = __builtin_bit_cast(u32x4, r0[m][bj]); a0 = (f32x4){bf_lo(rw.x), bf_hi(rw.x), bf_lo(rw.y), bf_hi(rw.y)}; a1 = (f32x4){bf_lo(rw.z), bf_hi(rw.z), bf_lo(rw.w), bf_hi(rw.w)};
;                         if (RES_SCALE) { const float rf = rfac[row]; a0 = a0 * rf; a1 = a1 * rf; } }
;                     else { a0 = r0[m][bj]; a1 = r1[m][bj]; }
;                     const f32x4 v0 = acc[ai][bj][m][0] + a0, v1 = acc[ai][bj][m][1] + a1;
;                     u32x4 w; w.x = cvt_pk_bf16(v0[0], v0[1]); w.y = cvt_pk_bf16(v0[2], v0[3]); w.z = cvt_pk_bf16(v1[0], v1[1]); w.w = cvt_pk_bf16(v1[2], v1[3]); *(u32x4*)(ob + off + bj * HALF) = w;
;                     ss += (v0[0] * v0[0] + v0[1] * v0[1]) + (v0[2] * v0[2] + v0[3] * v0[3]) + (v1[0] * v1[0] + v1[1] * v1[1]) + (v1[2] * v1[2] + v1[3] * v1[3]);
;                     if (rowmax) mx = fmaxf(mx, fmaxf(fmaxf(fmaxf(fabsf(v0[0]), fabsf(v0[1])), fmaxf(fabsf(v0[2]), fabsf(v0[3]))), fmaxf(fmaxf(fabsf(v1[0]), fabsf(v1[1])), fmaxf(fabsf(v1[2]), fabsf(v1[3]))))); }
;                 ss += __shfl_xor(ss, 16); ss += __shfl_xor(ss, 32); ssv[ai * 4 + m] = ss;
;                 if (rowmax) { mx = fmaxf(mx, __shfl_xor(mx, 16)); mx = fmaxf(mx, __shfl_xor(mx, 32)); } mxv[ai * 4 + m] = mx; }
;             asm volatile("" ::: "memory"); }
;         float s0 = 0.f, s1 = 0.f, m0 = 0.f, m1 = 0.f;
; #pragma unroll
;         for (int k = 0; k < 8; ++k) if ((k >> 1) == fq) { if (k & 1) { s1 = ssv[k]; m1 = mxv[k]; } else { s0 = ssv[k]; m0 = mxv[k]; } }
;         const int rq = row0 + (fq >> 1) * HALF + (fq & 1) * 32;
;         __hip_atomic_fetch_add(rowsq + rq, s0, __ATOMIC_RELAXED, __HIP_MEMORY_SCOPE_AGENT); __hip_atomic_fetch_add(rowsq + rq + 16, s1, __ATOMIC_RELAXED, __HIP_MEMORY_SCOPE_AGENT);
;         if (rowmax) { __hip_atomic_fetch_max(rowmax + rq, __float_as_uint(m0), __ATOMIC_RELAXED, __HIP_MEMORY_SCOPE_AGENT); __hip_atomic_fetch_max(rowmax + rq + 16, __float_as_uint(m1), __ATOMIC_RELAXED, __HIP_MEMORY_SCOPE_AGENT); }
	v_lshlrev_b32_e32 v248, 16, v206
	v_and_b32_e32 v249, 0xffff0000, v206
	v_lshlrev_b32_e32 v250, 16, v207
	v_and_b32_e32 v251, 0xffff0000, v207
	v_pk_add_f32 v[14:15], v[14:15], v[248:249]
	v_pk_add_f32 v[16:17], v[16:17], v[250:251]
	v_lshlrev_b32_e32 v248, 16, v208
	v_and_b32_e32 v249, 0xffff0000, v208
	v_lshlrev_b32_e32 v250, 16, v209
	v_and_b32_e32 v251, 0xffff0000, v209
	v_pk_add_f32 v[10:11], v[10:11], v[248:249]
	v_pk_add_f32 v[12:13], v[12:13], v[250:251]
	v_cvt_pk_bf16_f32 v206, v14, v15
	v_cvt_pk_bf16_f32 v207, v16, v17
	v_cvt_pk_bf16_f32 v208, v10, v11
	v_cvt_pk_bf16_f32 v209, v12, v13
	v_add_u32_e32 v246, 0x165800, v245
	global_store_dwordx4 v246, v[206:209], s[100:101] sc1
	v_mul_f32_e32 v247, v14, v14
	v_fmac_f32_e32 v247, v15, v15
	v_fmac_f32_e32 v247, v16, v16
	v_fmac_f32_e32 v247, v17, v17
	v_mul_f32_e32 v254, v10, v10
	v_fmac_f32_e32 v254, v11, v11
	v_fmac_f32_e32 v254, v12, v12
	v_fmac_f32_e32 v254, v13, v13
	v_max3_f32 v252, |v14|, |v15|, |v16|
	v_max3_f32 v252, |v17|, |v10|, v252
	v_max3_f32 v252, |v11|, |v12|, v252
	v_max_f32_e64 v252, |v13|, v252
	s_waitcnt vmcnt(15)
	v_lshlrev_b32_e32 v248, 16, v210
	v_and_b32_e32 v249, 0xffff0000, v210
	v_lshlrev_b32_e32 v250, 16, v211
	v_and_b32_e32 v251, 0xffff0000, v211
	v_pk_add_f32 v[6:7], v[6:7], v[248:249]
	v_pk_add_f32 v[8:9], v[8:9], v[250:251]
	v_lshlrev_b32_e32 v248, 16, v212
	v_and_b32_e32 v249, 0xffff0000, v212
	v_lshlrev_b32_e32 v250, 16, v213
	v_and_b32_e32 v251, 0xffff0000, v213
	v_pk_add_f32 v[2:3], v[2:3], v[248:249]
	v_pk_add_f32 v[4:5], v[4:5], v[250:251]
	v_cvt_pk_bf16_f32 v210, v6, v7
	v_cvt_pk_bf16_f32 v211, v8, v9
	v_cvt_pk_bf16_f32 v212, v2, v3
	v_cvt_pk_bf16_f32 v213, v4, v5
	v_add_u32_e32 v255, 0x165800, v245
	global_store_dwordx4 v255, v[210:213], s[100:101] offset:256 sc1
	v_fmac_f32_e32 v247, v6, v6
	v_fmac_f32_e32 v247, v7, v7
	v_fmac_f32_e32 v247, v8, v8
	v_fmac_f32_e32 v247, v9, v9
	v_fmac_f32_e32 v254, v2, v2
	v_fmac_f32_e32 v254, v3, v3
	v_fmac_f32_e32 v254, v4, v4
	v_fmac_f32_e32 v254, v5, v5
	v_max3_f32 v252, |v6|, |v7|, v252
	v_max_f32_e64 v252, |v8|, v252
	v_max3_f32 v252, |v9|, |v2|, v252
	v_max3_f32 v252, |v3|, |v4|, v252
	v_max_f32_e64 v252, |v5|, v252
	v_add_f32_e32 v14, v247, v254
	v_mov_b32_e32 v16, v252
	v_and_b32_e32 v255, 63, v0
	v_xor_b32_e32 v252, 16, v255
	v_xor_b32_e32 v253, 32, v255
	v_lshlrev_b32_e32 v252, 2, v252
	v_lshlrev_b32_e32 v253, 2, v253
	ds_bpermute_b32 v127, v252, v126
	ds_bpermute_b32 v129, v252, v128
	ds_bpermute_b32 v111, v252, v110
	ds_bpermute_b32 v113, v252, v112
	ds_bpermute_b32 v95, v252, v94
	ds_bpermute_b32 v97, v252, v96
	ds_bpermute_b32 v79, v252, v78
	ds_bpermute_b32 v81, v252, v80
	ds_bpermute_b32 v63, v252, v62
	ds_bpermute_b32 v65, v252, v64
	ds_bpermute_b32 v47, v252, v46
	ds_bpermute_b32 v49, v252, v48
	ds_bpermute_b32 v31, v252, v30
	ds_bpermute_b32 v33, v252, v32
	ds_bpermute_b32 v15, v252, v14
	ds_bpermute_b32 v17, v252, v16
	s_waitcnt lgkmcnt(0)
	v_add_f32_e32 v126, v126, v127
	v_max_f32_e32 v128, v128, v129
	v_add_f32_e32 v110, v110, v111
	v_max_f32_e32 v112, v112, v113
	v_add_f32_e32 v94, v94, v95
	v_max_f32_e32 v96, v96, v97
	v_add_f32_e32 v78, v78, v79
	v_max_f32_e32 v80, v80, v81
	v_add_f32_e32 v62, v62, v63
	v_max_f32_e32 v64, v64, v65
	v_add_f32_e32 v46, v46, v47
	v_max_f32_e32 v48, v48, v49
	v_add_f32_e32 v30, v30, v31
	v_max_f32_e32 v32, v32, v33
	v_add_f32_e32 v14, v14, v15
	v_max_f32_e32 v16, v16, v17
	ds_bpermute_b32 v127, v253, v126
	ds_bpermute_b32 v129, v253, v128
	ds_bpermute_b32 v111, v253, v110
	ds_bpermute_b32 v113, v253, v112
	ds_bpermute_b32 v95, v253, v94
	ds_bpermute_b32 v97, v253, v96
	ds_bpermute_b32 v79, v253, v78
	ds_bpermute_b32 v81, v253, v80
	ds_bpermute_b32 v63, v253, v62
	ds_bpermute_b32 v65, v253, v64
	ds_bpermute_b32 v47, v253, v46
	ds_bpermute_b32 v49, v253, v48
	ds_bpermute_b32 v31, v253, v30
	ds_bpermute_b32 v33, v253, v32
	ds_bpermute_b32 v15, v253, v14
	ds_bpermute_b32 v17, v253, v16
	s_waitcnt lgkmcnt(0)
	v_add_f32_e32 v126, v126, v127
	v_max_f32_e32 v128, v128, v129
	v_add_f32_e32 v110, v110, v111
	v_max_f32_e32 v112, v112, v113
	v_add_f32_e32 v94, v94, v95
	v_max_f32_e32 v96, v96, v97
	v_add_f32_e32 v78, v78, v79
	v_max_f32_e32 v80, v80, v81
	v_add_f32_e32 v62, v62, v63
	v_max_f32_e32 v64, v64, v65
	v_add_f32_e32 v46, v46, v47
	v_max_f32_e32 v48, v48, v49
	v_add_f32_e32 v30, v30, v31
	v_max_f32_e32 v32, v32, v33
	v_add_f32_e32 v14, v14, v15
	v_max_f32_e32 v16, v16, v17
	v_cndmask_b32_e64 v248, 0, v126, s[2:3]
	v_cndmask_b32_e64 v249, 0, v110, s[2:3]
	v_cndmask_b32_e64 v248, v248, v94, s[4:5]
	v_cndmask_b32_e64 v249, v249, v78, s[4:5]
	v_cndmask_b32_e64 v248, v248, v62, s[6:7]
	v_cndmask_b32_e64 v249, v249, v46, s[6:7]
	v_cndmask_b32_e64 v248, v248, v30, s[8:9]
	v_cndmask_b32_e64 v249, v249, v14, s[8:9]
	v_lshl_add_u32 v250, s72, 8, v181
	v_add_u32_e32 v250, v180, v250
	v_lshlrev_b32_e32 v250, 2, v250
	global_atomic_add_f32 v250, v248, s[54:55]
	global_atomic_add_f32 v250, v249, s[54:55] offset:64
	v_cndmask_b32_e64 v247, 0, v128, s[2:3]
	v_cndmask_b32_e64 v254, 0, v112, s[2:3]
	v_cndmask_b32_e64 v247, v247, v96, s[4:5]
	v_cndmask_b32_e64 v254, v254, v80, s[4:5]
	v_cndmask_b32_e64 v247, v247, v64, s[6:7]
	v_cndmask_b32_e64 v254, v254, v48, s[6:7]
	v_cndmask_b32_e64 v247, v247, v32, s[8:9]
	v_cndmask_b32_e64 v254, v254, v16, s[8:9]
	global_atomic_umax v250, v247, s[56:57]
	global_atomic_umax v250, v254, s[56:57] offset:64
	s_and_b64 vcc, exec, s[10:11]
	s_mov_b64 s[10:11], -1
	s_cbranch_vccnz .LBB0_992
	s_andn2_b64 vcc, exec, s[0:1]
	s_cbranch_vccnz .LBB0_991
	s_barrier
	s_branch .LBB0_991

; __device__ __forceinline__ unsigned cvt_pk_bf16(float lo, float hi) { unsigned r; asm volatile("v_cvt_pk_bf16_f32 %0, %1, %2" : "=v"(r) : "v"(lo), "v"(hi)); return r; }
; __device__ __forceinline__ float bf_lo(unsigned w) { return __uint_as_float(w << 16); }
;     __device__ __forceinline__ void operator()(EPI_ARGS) const {
;         const int row0 = u.pm * BM + wr * 64 + fr, col0 = u.pn * BM + wc * 32 + 8 * fq;
;         float ssv[8], mxv[8];
; #pragma unroll
;         for (int ai = 0; ai < 2; ++ai) {
;             f32x4 r0[4][2], r1[4][2];
; #pragma unroll
;             for (int m = 0; m < 4; ++m)
; #pragma unroll
;                 for (int bj = 0; bj < 2; ++bj) { const size_t off = (size_t)(row0 + ai * HALF + m * 16) * ldc + col0 + bj * HALF;
;                     if (RES_BF16) { const u32x4 rw = *(const u32x4*)((const bf16*)resid + off); r0[m][bj] = __builtin_bit_cast(f32x4, rw); }
;                     else { r0[m][bj] = *(const f32x4*)((const float*)resid + off); r1[m][bj] = *(const f32x4*)((const float*)resid + off + 4); } }
; #pragma unroll
;             for (int m = 0; m < 4; ++m) { const int row = row0 + ai * HALF + m * 16; const size_t off = (size_t)row * ldc + col0; float ss = 0.f, mx = 0.f;
; #pragma unroll
;                 for (int bj = 0; bj < 2; ++bj) {
;                     f32x4 a0, a1;
;                     if (RES_BF16) { const u32x4 rw = __builtin_bit_cast(u32x4, r0[m][bj]); a0 = (f32x4){bf_lo(rw.x), bf_hi(rw.x), bf_lo(rw.y), bf_hi(rw.y)}; a1 = (f32x4){bf_lo(rw.z), bf_hi(rw.z), bf_lo(rw.w), bf_hi(rw.w)};
;                         if (RES_SCALE) { const float rf = rfac[row]; a0 = a0 * rf; a1 = a1 * rf; } }
;                     else { a0 = r0[m][bj]; a1 = r1[m][bj]; }
;                     const f32x4 v0 = acc[ai][bj][m][0] + a0, v1 = acc[ai][bj][m][1] + a1;
;                     u32x4 w; w.x = cvt_pk_bf16(v0[0], v0[1]); w.y = cvt_pk_bf16(v0[2], v0[3]); w.z = cvt_pk_bf16(v1[0], v1[1]); w.w = cvt_pk_bf16(v1[2], v1[3]); *(u32x4*)(ob + off + bj * HALF) = w;
;                     ss += (v0[0] * v0[0] + v0[1] * v0[1]) + (v0[2] * v0[2] + v0[3] * v0[3]) + (v1[0] * v1[0] + v1[1] * v1[1]) + (v1[2] * v1[2] + v1[3] * v1[3]);
;                     if (rowmax) mx = fmaxf(mx, fmaxf(fmaxf(fmaxf(fabsf(v0[0]), fabsf(v0[1])), fmaxf(fabsf(v0[2]), fabsf(v0[3]))), fmaxf(fmaxf(fabsf(v1[0]), fabsf(v1[1])), fmaxf(fabsf(v1[2]), fabsf(v1[3]))))); }
.LBB0_1364:
	s_nop 7
	v_lshl_add_u32 v245, s72, 8, v157
	v_mul_u32_u24_e32 v245, 0x2080, v245
	v_lshl_or_b32 v246, s73, 8, v159
	v_lshl_add_u32 v245, v246, 1, v245
	global_load_dwordx4 v[130:133], v245, s[100:101]
	global_load_dwordx4 v[134:137], v245, s[100:101] offset:256
	v_add_u32_e32 v246, 0x20800, v245
	global_load_dwordx4 v[142:145], v246, s[100:101]
	global_load_dwordx4 v[146:149], v246, s[100:101] offset:256
	v_add_u32_e32 v255, 0x41000, v245
	global_load_dwordx4 v[150:153], v255, s[100:101]
	global_load_dwordx4 v[166:169], v255, s[100:101] offset:256
	v_add_u32_e32 v246, 0x61800, v245
	global_load_dwordx4 v[170:173], v246, s[100:101]
	global_load_dwordx4 v[174:177], v246, s[100:101] offset:256
	v_add_u32_e32 v255, 0x104000, v245
	global_load_dwordx4 v[178:181], v255, s[100:101]
	global_load_dwordx4 v[182:185], v255, s[100:101] offset:256
	v_add_u32_e32 v246, 0x124800, v245
	global_load_dwordx4 v[186:189], v246, s[100:101]
	global_load_dwordx4 v[190:193], v246, s[100:101] offset:256
	v_add_u32_e32 v255, 0x145000, v245
	global_load_dwordx4 v[194:197], v255, s[100:101]
	global_load_dwordx4 v[198:201], v255, s[100:101] offset:256
	v_add_u32_e32 v246, 0x165800, v245
	global_load_dwordx4 v[202:205], v246, s[100:101]
	global_load_dwordx4 v[206:209], v246, s[100:101] offset:256
	s_waitcnt vmcnt(15)
	v_lshlrev_b32_e32 v248, 16, v130
	v_and_b32_e32 v249, 0xffff0000, v130
	v_lshlrev_b32_e32 v250, 16, v131
	v_and_b32_e32 v251, 0xffff0000, v131
	v_pk_add_f32 v[126:127], v[126:127], v[248:249]
	v_pk_add_f32 v[128:129], v[128:129], v[250:251]
	v_lshlrev_b32_e32 v248, 16, v132
	v_and_b32_e32 v249, 0xffff0000, v132
	v_lshlrev_b32_e32 v250, 16, v133
	v_and_b32_e32 v251, 0xffff0000, v133
	v_pk_add_f32 v[122:123], v[122:123], v[248:249]
	v_pk_add_f32 v[124:125], v[124:125], v[250:251]
	v_cvt_pk_bf16_f32 v130, v126, v127
	v_cvt_pk_bf16_f32 v131, v128, v129
	v_cvt_pk_bf16_f32 v132, v122, v123
	v_cvt_pk_bf16_f32 v133, v124, v125
	global_store_dwordx4 v245, v[130:133], s[98:99] sc1
	v_mul_f32_e32 v247, v126, v126
	v_fmac_f32_e32 v247, v127, v127
	v_fmac_f32_e32 v247, v128, v128
	v_fmac_f32_e32 v247, v129, v129
	v_mul_f32_e32 v254, v122, v122
	v_fmac_f32_e32 v254, v123, v123
	v_fmac_f32_e32 v254, v124, v124
	v_fmac_f32_e32 v254, v125, v125
	s_waitcnt vmcnt(15)
	v_lshlrev_b32_e32 v248, 16, v134
	v_and_b32_e32 v249, 0xffff0000, v134
	v_lshlrev_b32_e32 v250, 16, v135
	v_and_b32_e32 v251, 0xffff0000, v135
	v_pk_add_f32 v[118:119], v[118:119], v[248:249]
	v_pk_add_f32 v[120:121], v[120:121], v[250:251]
	v_lshlrev_b32_e32 v248, 16, v136
	v_and_b32_e32 v249, 0xffff0000, v136
	v_lshlrev_b32_e32 v250, 16, v137
	v_and_b32_e32 v251, 0xffff0000, v137
	v_pk_add_f32 v[114:115], v[114:115], v[248:249]
	v_pk_add_f32 v[116:117], v[116:117], v[250:251]
	v_cvt_pk_bf16_f32 v134, v118, v119
	v_cvt_pk_bf16_f32 v135, v120, v121
	v_cvt_pk_bf16_f32 v136, v114, v115
	v_cvt_pk_bf16_f32 v137, v116, v117
	global_store_dwordx4 v245, v[134:137], s[98:99] offset:256 sc1
	v_fmac_f32_e32 v247, v118, v118
	v_fmac_f32_e32 v247, v119, v119
	v_fmac_f32_e32 v247, v120, v120
	v_fmac_f32_e32 v247, v121, v121
	v_fmac_f32_e32 v254, v114, v114
	v_fmac_f32_e32 v254, v115, v115
	v_fmac_f32_e32 v254, v116, v116
	v_fmac_f32_e32 v254, v117, v117
	v_add_f32_e32 v126, v247, v254
	s_waitcnt vmcnt(15)
	v_lshlrev_b32_e32 v248, 16, v142
	v_and_b32_e32 v249, 0xffff0000, v142
	v_lshlrev_b32_e32 v250, 16, v143
	v_and_b32_e32 v251, 0xffff0000, v143
	v_pk_add_f32 v[110:111], v[110:111], v[248:249]
	v_pk_add_f32 v[112:113], v[112:113], v[250:251]
	v_lshlrev_b32_e32 v248, 16, v144
	v_and_b32_e32 v249, 0xffff0000, v144
	v_lshlrev_b32_e32 v250, 16, v145
	v_and_b32_e32 v251, 0xffff0000, v145
	v_pk_add_f32 v[106:107], v[106:107], v[248:249]
	v_pk_add_f32 v[108:109], v[108:109], v[250:251]
	v_cvt_pk_bf16_f32 v142, v110, v111
	v_cvt_pk_bf16_f32 v143, v112, v113
	v_cvt_pk_bf16_f32 v144, v106, v107
	v_cvt_pk_bf16_f32 v145, v108, v109
	v_add_u32_e32 v246, 0x20800, v245
	global_store_dwordx4 v246, v[142:145], s[98:99] sc1
	v_mul_f32_e32 v247, v110, v110
	v_fmac_f32_e32 v247, v111, v111
	v_fmac_f32_e32 v247, v112, v112
	v_fmac_f32_e32 v247, v113, v113
	v_mul_f32_e32 v254, v106, v106
	v_fmac_f32_e32 v254, v107, v107
	v_fmac_f32_e32 v254, v108, v108
	v_fmac_f32_e32 v254, v109, v109
	s_waitcnt vmcnt(15)
	v_lshlrev_b32_e32 v248, 16, v146
	v_and_b32_e32 v249, 0xffff0000, v146
	v_lshlrev_b32_e32 v250, 16, v147
	v_and_b32_e32 v251, 0xffff0000, v147
	v_pk_add_f32 v[102:103], v[102:103], v[248:249]
	v_pk_add_f32 v[104:105], v[104:105], v[250:251]
	v_lshlrev_b32_e32 v248, 16, v148
	v_and_b32_e32 v249, 0xffff0000, v148
	v_lshlrev_b32_e32 v250, 16, v149
	v_and_b32_e32 v251, 0xffff0000, v149
	v_pk_add_f32 v[98:99], v[98:99], v[248:249]
	v_pk_add_f32 v[100:101], v[100:101], v[250:251]
	v_cvt_pk_bf16_f32 v146, v102, v103
	v_cvt_pk_bf16_f32 v147, v104, v105
	v_cvt_pk_bf16_f32 v148, v98, v99
	v_cvt_pk_bf16_f32 v149, v100, v101
	v_add_u32_e32 v255, 0x20800, v245
	global_store_dwordx4 v255, v[146:149], s[98:99] offset:256 sc1
	v_fmac_f32_e32 v247, v102, v102
	v_fmac_f32_e32 v247, v103, v103
	v_fmac_f32_e32 v247, v104, v104
	v_fmac_f32_e32 v247, v105, v105
	v_fmac_f32_e32 v254, v98, v98
	v_fmac_f32_e32 v254, v99, v99
	v_fmac_f32_e32 v254, v100, v100
	v_fmac_f32_e32 v254, v101, v101
	v_add_f32_e32 v110, v247, v254
	s_waitcnt vmcnt(15)
; __device__ __forceinline__ unsigned cvt_pk_bf16(float lo, float hi) { unsigned r; asm volatile("v_cvt_pk_bf16_f32 %0, %1, %2" : "=v"(r) : "v"(lo), "v"(hi)); return r; }
; __device__ __forceinline__ float bf_lo(unsigned w) { return __uint_as_float(w << 16); }
; __device__ __forceinline__ float bf_hi(unsigned w) { return __uint_as_float(w & 0xffff0000u); }
;     __device__ __forceinline__ void operator()(EPI_ARGS) const {
;     ...
;             for (int m = 0; m < 4; ++m) { const int row = row0 + ai * HALF + m * 16; const size_t off = (size_t)row * ldc + col0; float ss = 0.f, mx = 0.f;
; #pragma unroll
;                 for (int bj = 0; bj < 2; ++bj) {
;                     f32x4 a0, a1;
;                     if (RES_BF16) { const u32x4 rw = __builtin_bit_cast(u32x4, r0[m][bj]); a0 = (f32x4){bf_lo(rw.x), bf_hi(rw.x), bf_lo(rw.y), bf_hi(rw.y)}; a1 = (f32x4){bf_lo(rw.z), bf_hi(rw.z), bf_lo(rw.w), bf_hi(rw.w)};
;                         if (RES_SCALE) { const float rf = rfac[row]; a0 = a0 * rf; a1 = a1 * rf; } }
;                     else { a0 = r0[m][bj]; a1 = r1[m][bj]; }
;                     const f32x4 v0 = acc[ai][bj][m][0] + a0, v1 = acc[ai][bj][m][1] + a1;
;                     u32x4 w; w.x = cvt_pk_bf16(v0[0], v0[1]); w.y = cvt_pk_bf16(v0[2], v0[3]); w.z = cvt_pk_bf16(v1[0], v1[1]); w.w = cvt_pk_bf16(v1[2], v1[3]); *(u32x4*)(ob + off + bj * HALF) = w;
;                     ss += (v0[0] * v0[0] + v0[1] * v0[1]) + (v0[2] * v0[2] + v0[3] * v0[3]) + (v1[0] * v1[0] + v1[1] * v1[1]) + (v1[2] * v1[2] + v1[3] * v1[3]);
;                     if (rowmax) mx = fmaxf(mx, fmaxf(fmaxf(fmaxf(fabsf(v0[0]), fabsf(v0[1])), fmaxf(fabsf(v0[2]), fabsf(v0[3]))), fmaxf(fmaxf(fabsf(v1[0]), fabsf(v1[1])), fmaxf(fabsf(v1[2]), fabsf(v1[3]))))); }
	v_lshlrev_b32_e32 v248, 16, v150
	v_and_b32_e32 v249, 0xffff0000, v150
	v_lshlrev_b32_e32 v250, 16, v151
	v_and_b32_e32 v251, 0xffff0000, v151
	v_pk_add_f32 v[94:95], v[94:95], v[248:249]
	v_pk_add_f32 v[96:97], v[96:97], v[250:251]
	v_lshlrev_b32_e32 v248, 16, v152
	v_and_b32_e32 v249, 0xffff0000, v152
	v_lshlrev_b32_e32 v250, 16, v153
	v_and_b32_e32 v251, 0xffff0000, v153
	v_pk_add_f32 v[90:91], v[90:91], v[248:249]
	v_pk_add_f32 v[92:93], v[92:93], v[250:251]
	v_cvt_pk_bf16_f32 v150, v94, v95
	v_cvt_pk_bf16_f32 v151, v96, v97
	v_cvt_pk_bf16_f32 v152, v90, v91
	v_cvt_pk_bf16_f32 v153, v92, v93
	v_add_u32_e32 v246, 0x41000, v245
	global_store_dwordx4 v246, v[150:153], s[98:99] sc1
	v_mul_f32_e32 v247, v94, v94
	v_fmac_f32_e32 v247, v95, v95
	v_fmac_f32_e32 v247, v96, v96
	v_fmac_f32_e32 v247, v97, v97
	v_mul_f32_e32 v254, v90, v90
	v_fmac_f32_e32 v254, v91, v91
	v_fmac_f32_e32 v254, v92, v92
	v_fmac_f32_e32 v254, v93, v93
	s_waitcnt vmcnt(15)
	v_lshlrev_b32_e32 v248, 16, v166
	v_and_b32_e32 v249, 0xffff0000, v166
	v_lshlrev_b32_e32 v250, 16, v167
	v_and_b32_e32 v251, 0xffff0000, v167
	v_pk_add_f32 v[86:87], v[86:87], v[248:249]
	v_pk_add_f32 v[88:89], v[88:89], v[250:251]
	v_lshlrev_b32_e32 v248, 16, v168
	v_and_b32_e32 v249, 0xffff0000, v168
	v_lshlrev_b32_e32 v250, 16, v169
	v_and_b32_e32 v251, 0xffff0000, v169
	v_pk_add_f32 v[82:83], v[82:83], v[248:249]
	v_pk_add_f32 v[84:85], v[84:85], v[250:251]
	v_cvt_pk_bf16_f32 v166, v86, v87
	v_cvt_pk_bf16_f32 v167, v88, v89
	v_cvt_pk_bf16_f32 v168, v82, v83
	v_cvt_pk_bf16_f32 v169, v84, v85
	v_add_u32_e32 v255, 0x41000, v245
	global_store_dwordx4 v255, v[166:169], s[98:99] offset:256 sc1
	v_fmac_f32_e32 v247, v86, v86
	v_fmac_f32_e32 v247, v87, v87
	v_fmac_f32_e32 v247, v88, v88
	v_fmac_f32_e32 v247, v89, v89
	v_fmac_f32_e32 v254, v82, v82
	v_fmac_f32_e32 v254, v83, v83
	v_fmac_f32_e32 v254, v84, v84
	v_fmac_f32_e32 v254, v85, v85
	v_add_f32_e32 v94, v247, v254
	s_waitcnt vmcnt(15)
	v_lshlrev_b32_e32 v248, 16, v170
	v_and_b32_e32 v249, 0xffff0000, v170
	v_lshlrev_b32_e32 v250, 16, v171
	v_and_b32_e32 v251, 0xffff0000, v171
	v_pk_add_f32 v[78:79], v[78:79], v[248:249]
	v_pk_add_f32 v[80:81], v[80:81], v[250:251]
	v_lshlrev_b32_e32 v248, 16, v172
	v_and_b32_e32 v249, 0xffff0000, v172
	v_lshlrev_b32_e32 v250, 16, v173
	v_and_b32_e32 v251, 0xffff0000, v173
	v_pk_add_f32 v[74:75], v[74:75], v[248:249]
	v_pk_add_f32 v[76:77], v[76:77], v[250:251]
	v_cvt_pk_bf16_f32 v170, v78, v79
	v_cvt_pk_bf16_f32 v171, v80, v81
	v_cvt_pk_bf16_f32 v172, v74, v75
	v_cvt_pk_bf16_f32 v173, v76, v77
	v_add_u32_e32 v246, 0x61800, v245
	global_store_dwordx4 v246, v[170:173], s[98:99] sc1
	v_mul_f32_e32 v247, v78, v78
	v_fmac_f32_e32 v247, v79, v79
	v_fmac_f32_e32 v247, v80, v80
	v_fmac_f32_e32 v247, v81, v81
	v_mul_f32_e32 v254, v74, v74
	v_fmac_f32_e32 v254, v75, v75
	v_fmac_f32_e32 v254, v76, v76
	v_fmac_f32_e32 v254, v77, v77
	s_waitcnt vmcnt(15)
	v_lshlrev_b32_e32 v248, 16, v174
	v_and_b32_e32 v249, 0xffff0000, v174
	v_lshlrev_b32_e32 v250, 16, v175
	v_and_b32_e32 v251, 0xffff0000, v175
	v_pk_add_f32 v[70:71], v[70:71], v[248:249]
	v_pk_add_f32 v[72:73], v[72:73], v[250:251]
	v_lshlrev_b32_e32 v248, 16, v176
	v_and_b32_e32 v249, 0xffff0000, v176
	v_lshlrev_b32_e32 v250, 16, v177
	v_and_b32_e32 v251, 0xffff0000, v177
	v_pk_add_f32 v[66:67], v[66:67], v[248:249]
	v_pk_add_f32 v[68:69], v[68:69], v[250:251]
	v_cvt_pk_bf16_f32 v174, v70, v71
	v_cvt_pk_bf16_f32 v175, v72, v73
	v_cvt_pk_bf16_f32 v176, v66, v67
	v_cvt_pk_bf16_f32 v177, v68, v69
	v_add_u32_e32 v255, 0x61800, v245
	global_store_dwordx4 v255, v[174:177], s[98:99] offset:256 sc1
	v_fmac_f32_e32 v247, v70, v70
	v_fmac_f32_e32 v247, v71, v71
	v_fmac_f32_e32 v247, v72, v72
	v_fmac_f32_e32 v247, v73, v73
	v_fmac_f32_e32 v254, v66, v66
	v_fmac_f32_e32 v254, v67, v67
	v_fmac_f32_e32 v254, v68, v68
	v_fmac_f32_e32 v254, v69, v69
	v_add_f32_e32 v78, v247, v254
	s_waitcnt vmcnt(15)
	v_lshlrev_b32_e32 v248, 16, v178
	v_and_b32_e32 v249, 0xffff0000, v178
	v_lshlrev_b32_e32 v250, 16, v179
	v_and_b32_e32 v251, 0xffff0000, v179
	v_pk_add_f32 v[62:63], v[62:63], v[248:249]
	v_pk_add_f32 v[64:65], v[64:65], v[250:251]
	v_lshlrev_b32_e32 v248, 16, v180
	v_and_b32_e32 v249, 0xffff0000, v180
	v_lshlrev_b32_e32 v250, 16, v181
	v_and_b32_e32 v251, 0xffff0000, v181
	v_pk_add_f32 v[58:59], v[58:59], v[248:249]
	v_pk_add_f32 v[60:61], v[60:61], v[250:251]
	v_cvt_pk_bf16_f32 v178, v62, v63
	v_cvt_pk_bf16_f32 v179, v64, v65
	v_cvt_pk_bf16_f32 v180, v58, v59
	v_cvt_pk_bf16_f32 v181, v60, v61
	v_add_u32_e32 v246, 0x104000, v245
	global_store_dwordx4 v246, v[178:181], s[98:99] sc1
	v_mul_f32_e32 v247, v62, v62
	v_fmac_f32_e32 v247, v63, v63
	v_fmac_f32_e32 v247, v64, v64
	v_fmac_f32_e32 v247, v65, v65
	v_mul_f32_e32 v254, v58, v58
	v_fmac_f32_e32 v254, v59, v59
	v_fmac_f32_e32 v254, v60, v60
	v_fmac_f32_e32 v254, v61, v61
	s_waitcnt vmcnt(15)
	v_lshlrev_b32_e32 v248, 16, v182
	v_and_b32_e32 v249, 0xffff0000, v182
	v_lshlrev_b32_e32 v250, 16, v183
	v_and_b32_e32 v251, 0xffff0000, v183
	v_pk_add_f32 v[54:55], v[54:55], v[248:249]
	v_pk_add_f32 v[56:57], v[56:57], v[250:251]
	v_lshlrev_b32_e32 v248, 16, v184
	v_and_b32_e32 v249, 0xffff0000, v184
	v_lshlrev_b32_e32 v250, 16, v185
	v_and_b32_e32 v251, 0xffff0000, v185
	v_pk_add_f32 v[50:51], v[50:51], v[248:249]
	v_pk_add_f32 v[52:53], v[52:53], v[250:251]
	v_cvt_pk_bf16_f32 v182, v54, v55
	v_cvt_pk_bf16_f32 v183, v56, v57
	v_cvt_pk_bf16_f32 v184, v50, v51
	v_cvt_pk_bf16_f32 v185, v52, v53
	v_add_u32_e32 v255, 0x104000, v245
	global_store_dwordx4 v255, v[182:185], s[98:99] offset:256 sc1
	v_fmac_f32_e32 v247, v54, v54
	v_fmac_f32_e32 v247, v55, v55
	v_fmac_f32_e32 v247, v56, v56
	v_fmac_f32_e32 v247, v57, v57
	v_fmac_f32_e32 v254, v50, v50
	v_fmac_f32_e32 v254, v51, v51
	v_fmac_f32_e32 v254, v52, v52
	v_fmac_f32_e32 v254, v53, v53
	v_add_f32_e32 v62, v247, v254
	s_waitcnt vmcnt(15)
; __device__ __forceinline__ unsigned cvt_pk_bf16(float lo, float hi) { unsigned r; asm volatile("v_cvt_pk_bf16_f32 %0, %1, %2" : "=v"(r) : "v"(lo), "v"(hi)); return r; }
; __device__ __forceinline__ float bf_lo(unsigned w) { return __uint_as_float(w << 16); }
; __device__ __forceinline__ float bf_hi(unsigned w) { return __uint_as_float(w & 0xffff0000u); }
;     __device__ __forceinline__ void operator()(EPI_ARGS) const {
;     ...
;             for (int m = 0; m < 4; ++m) { const int row = row0 + ai * HALF + m * 16; const size_t off = (size_t)row * ldc + col0; float ss = 0.f, mx = 0.f;
; #pragma unroll
;                 for (int bj = 0; bj < 2; ++bj) {
;                     f32x4 a0, a1;
;                     if (RES_BF16) { const u32x4 rw = __builtin_bit_cast(u32x4, r0[m][bj]); a0 = (f32x4){bf_lo(rw.x), bf_hi(rw.x), bf_lo(rw.y), bf_hi(rw.y)}; a1 = (f32x4){bf_lo(rw.z), bf_hi(rw.z), bf_lo(rw.w), bf_hi(rw.w)};
;                         if (RES_SCALE) { const float rf = rfac[row]; a0 = a0 * rf; a1 = a1 * rf; } }
;                     else { a0 = r0[m][bj]; a1 = r1[m][bj]; }
;                     const f32x4 v0 = acc[ai][bj][m][0] + a0, v1 = acc[ai][bj][m][1] + a1;
;                     u32x4 w; w.x = cvt_pk_bf16(v0[0], v0[1]); w.y = cvt_pk_bf16(v0[2], v0[3]); w.z = cvt_pk_bf16(v1[0], v1[1]); w.w = cvt_pk_bf16(v1[2], v1[3]); *(u32x4*)(ob + off + bj * HALF) = w;
;                     ss += (v0[0] * v0[0] + v0[1] * v0[1]) + (v0[2] * v0[2] + v0[3] * v0[3]) + (v1[0] * v1[0] + v1[1] * v1[1]) + (v1[2] * v1[2] + v1[3] * v1[3]);
;                     if (rowmax) mx = fmaxf(mx, fmaxf(fmaxf(fmaxf(fabsf(v0[0]), fabsf(v0[1])), fmaxf(fabsf(v0[2]), fabsf(v0[3]))), fmaxf(fmaxf(fabsf(v1[0]), fabsf(v1[1])), fmaxf(fabsf(v1[2]), fabsf(v1[3]))))); }
	v_lshlrev_b32_e32 v248, 16, v186
	v_and_b32_e32 v249, 0xffff0000, v186
	v_lshlrev_b32_e32 v250, 16, v187
	v_and_b32_e32 v251, 0xffff0000, v187
	v_pk_add_f32 v[46:47], v[46:47], v[248:249]
	v_pk_add_f32 v[48:49], v[48:49], v[250:251]
	v_lshlrev_b32_e32 v248, 16, v188
	v_and_b32_e32 v249, 0xffff0000, v188
	v_lshlrev_b32_e32 v250, 16, v189
	v_and_b32_e32 v251, 0xffff0000, v189
	v_pk_add_f32 v[42:43], v[42:43], v[248:249]
	v_pk_add_f32 v[44:45], v[44:45], v[250:251]
	v_cvt_pk_bf16_f32 v186, v46, v47
	v_cvt_pk_bf16_f32 v187, v48, v49
	v_cvt_pk_bf16_f32 v188, v42, v43
	v_cvt_pk_bf16_f32 v189, v44, v45
	v_add_u32_e32 v246, 0x124800, v245
	global_store_dwordx4 v246, v[186:189], s[98:99] sc1
	v_mul_f32_e32 v247, v46, v46
	v_fmac_f32_e32 v247, v47, v47
	v_fmac_f32_e32 v247, v48, v48
	v_fmac_f32_e32 v247, v49, v49
	v_mul_f32_e32 v254, v42, v42
	v_fmac_f32_e32 v254, v43, v43
	v_fmac_f32_e32 v254, v44, v44
	v_fmac_f32_e32 v254, v45, v45
	s_waitcnt vmcnt(15)
	v_lshlrev_b32_e32 v248, 16, v190
	v_and_b32_e32 v249, 0xffff0000, v190
	v_lshlrev_b32_e32 v250, 16, v191
	v_and_b32_e32 v251, 0xffff0000, v191
	v_pk_add_f32 v[38:39], v[38:39], v[248:249]
	v_pk_add_f32 v[40:41], v[40:41], v[250:251]
	v_lshlrev_b32_e32 v248, 16, v192
	v_and_b32_e32 v249, 0xffff0000, v192
	v_lshlrev_b32_e32 v250, 16, v193
	v_and_b32_e32 v251, 0xffff0000, v193
	v_pk_add_f32 v[34:35], v[34:35], v[248:249]
	v_pk_add_f32 v[36:37], v[36:37], v[250:251]
	v_cvt_pk_bf16_f32 v190, v38, v39
	v_cvt_pk_bf16_f32 v191, v40, v41
	v_cvt_pk_bf16_f32 v192, v34, v35
	v_cvt_pk_bf16_f32 v193, v36, v37
	v_add_u32_e32 v255, 0x124800, v245
	global_store_dwordx4 v255, v[190:193], s[98:99] offset:256 sc1
	v_fmac_f32_e32 v247, v38, v38
	v_fmac_f32_e32 v247, v39, v39
	v_fmac_f32_e32 v247, v40, v40
	v_fmac_f32_e32 v247, v41, v41
	v_fmac_f32_e32 v254, v34, v34
	v_fmac_f32_e32 v254, v35, v35
	v_fmac_f32_e32 v254, v36, v36
	v_fmac_f32_e32 v254, v37, v37
	v_add_f32_e32 v46, v247, v254
	s_waitcnt vmcnt(15)
	v_lshlrev_b32_e32 v248, 16, v194
	v_and_b32_e32 v249, 0xffff0000, v194
	v_lshlrev_b32_e32 v250, 16, v195
	v_and_b32_e32 v251, 0xffff0000, v195
	v_pk_add_f32 v[30:31], v[30:31], v[248:249]
	v_pk_add_f32 v[32:33], v[32:33], v[250:251]
	v_lshlrev_b32_e32 v248, 16, v196
	v_and_b32_e32 v249, 0xffff0000, v196
	v_lshlrev_b32_e32 v250, 16, v197
	v_and_b32_e32 v251, 0xffff0000, v197
	v_pk_add_f32 v[26:27], v[26:27], v[248:249]
	v_pk_add_f32 v[28:29], v[28:29], v[250:251]
	v_cvt_pk_bf16_f32 v194, v30, v31
	v_cvt_pk_bf16_f32 v195, v32, v33
	v_cvt_pk_bf16_f32 v196, v26, v27
	v_cvt_pk_bf16_f32 v197, v28, v29
	v_add_u32_e32 v246, 0x145000, v245
	global_store_dwordx4 v246, v[194:197], s[98:99] sc1
	v_mul_f32_e32 v247, v30, v30
	v_fmac_f32_e32 v247, v31, v31
	v_fmac_f32_e32 v247, v32, v32
	v_fmac_f32_e32 v247, v33, v33
	v_mul_f32_e32 v254, v26, v26
	v_fmac_f32_e32 v254, v27, v27
	v_fmac_f32_e32 v254, v28, v28
	v_fmac_f32_e32 v254, v29, v29
	s_waitcnt vmcnt(15)
	v_lshlrev_b32_e32 v248, 16, v198
	v_and_b32_e32 v249, 0xffff0000, v198
	v_lshlrev_b32_e32 v250, 16, v199
	v_and_b32_e32 v251, 0xffff0000, v199
	v_pk_add_f32 v[22:23], v[22:23], v[248:249]
	v_pk_add_f32 v[24:25], v[24:25], v[250:251]
	v_lshlrev_b32_e32 v248, 16, v200
	v_and_b32_e32 v249, 0xffff0000, v200
	v_lshlrev_b32_e32 v250, 16, v201
	v_and_b32_e32 v251, 0xffff0000, v201
	v_pk_add_f32 v[18:19], v[18:19], v[248:249]
	v_pk_add_f32 v[20:21], v[20:21], v[250:251]
	v_cvt_pk_bf16_f32 v198, v22, v23
	v_cvt_pk_bf16_f32 v199, v24, v25
	v_cvt_pk_bf16_f32 v200, v18, v19
	v_cvt_pk_bf16_f32 v201, v20, v21
	v_add_u32_e32 v255, 0x145000, v245
	global_store_dwordx4 v255, v[198:201], s[98:99] offset:256 sc1
	v_fmac_f32_e32 v247, v22, v22
	v_fmac_f32_e32 v247, v23, v23
	v_fmac_f32_e32 v247, v24, v24
	v_fmac_f32_e32 v247, v25, v25
	v_fmac_f32_e32 v254, v18, v18
	v_fmac_f32_e32 v254, v19, v19
	v_fmac_f32_e32 v254, v20, v20
	v_fmac_f32_e32 v254, v21, v21
	v_add_f32_e32 v30, v247, v254
	s_waitcnt vmcnt(15)
;     __device__ __forceinline__ void operator()(EPI_ARGS) const {
;     ...
;             for (int m = 0; m < 4; ++m) { const int row = row0 + ai * HALF + m * 16; const size_t off = (size_t)row * ldc + col0; float ss = 0.f, mx = 0.f;
; #pragma unroll
;                 for (int bj = 0; bj < 2; ++bj) {
;                     f32x4 a0, a1;
;                     if (RES_BF16) { const u32x4 rw = __builtin_bit_cast(u32x4, r0[m][bj]); a0 = (f32x4){bf_lo(rw.x), bf_hi(rw.x), bf_lo(rw.y), bf_hi(rw.y)}; a1 = (f32x4){bf_lo(rw.z), bf_hi(rw.z), bf_lo(rw.w), bf_hi(rw.w)};
;                         if (RES_SCALE) { const float rf = rfac[row]; a0 = a0 * rf; a1 = a1 * rf; } }
;                     else { a0 = r0[m][bj]; a1 = r1[m][bj]; }
;                     const f32x4 v0 = acc[ai][bj][m][0] + a0, v1 = acc[ai][bj][m][1] + a1;
;                     u32x4 w; w.x = cvt_pk_bf16(v0[0], v0[1]); w.y = cvt_pk_bf16(v0[2], v0[3]); w.z = cvt_pk_bf16(v1[0], v1[1]); w.w = cvt_pk_bf16(v1[2], v1[3]); *(u32x4*)(ob + off + bj * HALF) = w;
;                     ss += (v0[0] * v0[0] + v0[1] * v0[1]) + (v0[2] * v0[2] + v0[3] * v0[3]) + (v1[0] * v1[0] + v1[1] * v1[1]) + (v1[2] * v1[2] + v1[3] * v1[3]);
;                     if (rowmax) mx = fmaxf(mx, fmaxf(fmaxf(fmaxf(fabsf(v0[0]), fabsf(v0[1])), fmaxf(fabsf(v0[2]), fabsf(v0[3]))), fmaxf(fmaxf(fabsf(v1[0]), fabsf(v1[1])), fmaxf(fabsf(v1[2]), fabsf(v1[3]))))); }
;                 ss += __shfl_xor(ss, 16); ss += __shfl_xor(ss, 32); ssv[ai * 4 + m] = ss;
;                 if (rowmax) { mx = fmaxf(mx, __shfl_xor(mx, 16)); mx = fmaxf(mx, __shfl_xor(mx, 32)); } mxv[ai * 4 + m] = mx; }
;             asm volatile("" ::: "memory"); }
;         float s0 = 0.f, s1 = 0.f, m0 = 0.f, m1 = 0.f;
; #pragma unroll
;         for (int k = 0; k < 8; ++k) if ((k >> 1) == fq) { if (k & 1) { s1 = ssv[k]; m1 = mxv[k]; } else { s0 = ssv[k]; m0 = mxv[k]; } }
;         const int rq = row0 + (fq >> 1) * HALF + (fq & 1) * 32;
;         __hip_atomic_fetch_add(rowsq + rq, s0, __ATOMIC_RELAXED, __HIP_MEMORY_SCOPE_AGENT); __hip_atomic_fetch_add(rowsq + rq + 16, s1, __ATOMIC_RELAXED, __HIP_MEMORY_SCOPE_AGENT);
;         if (rowmax) { __hip_atomic_fetch_max(rowmax + rq, __float_as_uint(m0), __ATOMIC_RELAXED, __HIP_MEMORY_SCOPE_AGENT); __hip_atomic_fetch_max(rowmax + rq + 16, __float_as_uint(m1), __ATOMIC_RELAXED, __HIP_MEMORY_SCOPE_AGENT); }
	v_lshlrev_b32_e32 v248, 16, v202
	v_and_b32_e32 v249, 0xffff0000, v202
	v_lshlrev_b32_e32 v250, 16, v203
	v_and_b32_e32 v251, 0xffff0000, v203
	v_pk_add_f32 v[14:15], v[14:15], v[248:249]
	v_pk_add_f32 v[16:17], v[16:17], v[250:251]
	v_lshlrev_b32_e32 v248, 16, v204
	v_and_b32_e32 v249, 0xffff0000, v204
	v_lshlrev_b32_e32 v250, 16, v205
	v_and_b32_e32 v251, 0xffff0000, v205
	v_pk_add_f32 v[10:11], v[10:11], v[248:249]
	v_pk_add_f32 v[12:13], v[12:13], v[250:251]
	v_cvt_pk_bf16_f32 v202, v14, v15
	v_cvt_pk_bf16_f32 v203, v16, v17
	v_cvt_pk_bf16_f32 v204, v10, v11
	v_cvt_pk_bf16_f32 v205, v12, v13
	v_add_u32_e32 v246, 0x165800, v245
	global_store_dwordx4 v246, v[202:205], s[98:99] sc1
	v_mul_f32_e32 v247, v14, v14
	v_fmac_f32_e32 v247, v15, v15
	v_fmac_f32_e32 v247, v16, v16
	v_fmac_f32_e32 v247, v17, v17
	v_mul_f32_e32 v254, v10, v10
	v_fmac_f32_e32 v254, v11, v11
	v_fmac_f32_e32 v254, v12, v12
	v_fmac_f32_e32 v254, v13, v13
	s_waitcnt vmcnt(15)
	v_lshlrev_b32_e32 v248, 16, v206
	v_and_b32_e32 v249, 0xffff0000, v206
	v_lshlrev_b32_e32 v250, 16, v207
	v_and_b32_e32 v251, 0xffff0000, v207
	v_pk_add_f32 v[6:7], v[6:7], v[248:249]
	v_pk_add_f32 v[8:9], v[8:9], v[250:251]
	v_lshlrev_b32_e32 v248, 16, v208
	v_and_b32_e32 v249, 0xffff0000, v208
	v_lshlrev_b32_e32 v250, 16, v209
	v_and_b32_e32 v251, 0xffff0000, v209
	v_pk_add_f32 v[2:3], v[2:3], v[248:249]
	v_pk_add_f32 v[4:5], v[4:5], v[250:251]
	v_cvt_pk_bf16_f32 v206, v6, v7
	v_cvt_pk_bf16_f32 v207, v8, v9
	v_cvt_pk_bf16_f32 v208, v2, v3
	v_cvt_pk_bf16_f32 v209, v4, v5
	v_add_u32_e32 v255, 0x165800, v245
	global_store_dwordx4 v255, v[206:209], s[98:99] offset:256 sc1
	v_fmac_f32_e32 v247, v6, v6
	v_fmac_f32_e32 v247, v7, v7
	v_fmac_f32_e32 v247, v8, v8
	v_fmac_f32_e32 v247, v9, v9
	v_fmac_f32_e32 v254, v2, v2
	v_fmac_f32_e32 v254, v3, v3
	v_fmac_f32_e32 v254, v4, v4
	v_fmac_f32_e32 v254, v5, v5
	v_add_f32_e32 v14, v247, v254
	v_and_b32_e32 v255, 63, v0
	v_xor_b32_e32 v252, 16, v255
	v_xor_b32_e32 v253, 32, v255
	v_lshlrev_b32_e32 v252, 2, v252
	v_lshlrev_b32_e32 v253, 2, v253
	ds_bpermute_b32 v127, v252, v126
	ds_bpermute_b32 v111, v252, v110
	ds_bpermute_b32 v95, v252, v94
	ds_bpermute_b32 v79, v252, v78
	ds_bpermute_b32 v63, v252, v62
	ds_bpermute_b32 v47, v252, v46
	ds_bpermute_b32 v31, v252, v30
	ds_bpermute_b32 v15, v252, v14
	s_waitcnt lgkmcnt(0)
	v_add_f32_e32 v126, v126, v127
	v_add_f32_e32 v110, v110, v111
	v_add_f32_e32 v94, v94, v95
	v_add_f32_e32 v78, v78, v79
	v_add_f32_e32 v62, v62, v63
	v_add_f32_e32 v46, v46, v47
	v_add_f32_e32 v30, v30, v31
	v_add_f32_e32 v14, v14, v15
	ds_bpermute_b32 v127, v253, v126
	ds_bpermute_b32 v111, v253, v110
	ds_bpermute_b32 v95, v253, v94
	ds_bpermute_b32 v79, v253, v78
	ds_bpermute_b32 v63, v253, v62
	ds_bpermute_b32 v47, v253, v46
	ds_bpermute_b32 v31, v253, v30
	ds_bpermute_b32 v15, v253, v14
	s_waitcnt lgkmcnt(0)
	v_add_f32_e32 v126, v126, v127
	v_add_f32_e32 v110, v110, v111
	v_add_f32_e32 v94, v94, v95
	v_add_f32_e32 v78, v78, v79
	v_add_f32_e32 v62, v62, v63
	v_add_f32_e32 v46, v46, v47
	v_add_f32_e32 v30, v30, v31
	v_add_f32_e32 v14, v14, v15
	v_cndmask_b32_e64 v248, 0, v126, s[2:3]
	v_cndmask_b32_e64 v249, 0, v110, s[2:3]
	v_cndmask_b32_e64 v248, v248, v94, s[4:5]
	v_cndmask_b32_e64 v249, v249, v78, s[4:5]
	v_cndmask_b32_e64 v248, v248, v62, s[6:7]
	v_cndmask_b32_e64 v249, v249, v46, s[6:7]
	v_cndmask_b32_e64 v248, v248, v30, s[8:9]
	v_cndmask_b32_e64 v249, v249, v14, s[8:9]
	v_lshl_add_u32 v250, s72, 8, v157
	v_add_u32_e32 v250, v158, v250
	v_lshlrev_b32_e32 v250, 2, v250
	global_atomic_add_f32 v250, v248, s[34:35]
	global_atomic_add_f32 v250, v249, s[34:35] offset:64
	s_and_b64 vcc, exec, s[10:11]
	s_mov_b64 s[10:11], -1
	s_cbranch_vccnz .LBB0_1349
	s_andn2_b64 vcc, exec, s[0:1]
	s_cbranch_vccnz .LBB0_1348
	s_barrier
	s_branch .LBB0_1348
